# scan body rewrite + XCD-affine task maps for scan and hg_seq (q4/vq siblings share an L2)
# speedup vs baseline: 1.0077x; 1.0000x over previous
; __device__ __forceinline__ void rwkv_scan(const Params& p, LAS unsigned char* lds, int rowbase, int T, int h, int q4, const float* S0, float* Sout) {
;     const int tid = opaque_tid(), lane = tid & 63, w = __builtin_amdgcn_readfirstlane(tid >> 6), rowl = lane >> 4, seg = lane & 15; const int vloc = (w & 3) * 4 + rowl, vrow = q4 * 16 + vloc;
;     unsigned char* ws = p.ws;
;     const float* decay = p.out; const bf16_t* kk = (const bf16_t*)((const unsigned char*)p.out + 68157440); const bf16_t* kka = (const bf16_t*)((const unsigned char*)p.out + 68157440 + HALF512);
;     const bf16_t* kp = (const bf16_t*)(ws + WS_PRW); const bf16_t* rb = (const bf16_t*)(ws + WS_A); const bf16_t* vb = (const bf16_t*)(ws + WS_A + HALF512);
;     bf16_t* ob = (bf16_t*)(ws + WS_B);
;     const bool comp = w < 4;
;     f32x4 S = (f32x4){0.f, 0.f, 0.f, 0.f};
;     if (comp && S0) S = *(const f32x4*)(S0 + vrow * 64 + seg * 4);
;     constexpr int BUF = 43008;
;     const bool ldr = w >= 4; const int lt = tid & 255, lstep = lt >> 4, lj = lt & 15;
;     f32x4 gd[2]; u32x2 gk[2], ga[2], gp[2], gr[2], gv[2];
;     auto gload = [&](int c) {
;         if (ldr) {
; #pragma unroll
;             for (int q = 0; q < 2; ++q) {
;                 const size_t row = (size_t)(rowbase + c * 32 + lstep + q * 16); const size_t o = row * 512 + h * 64 + lj * 4;
;                 gd[q] = *(const f32x4*)(decay + o); gk[q] = *(const u32x2*)(kk + o); ga[q] = *(const u32x2*)(kka + o); gp[q] = *(const u32x2*)(kp + o); gr[q] = *(const u32x2*)(rb + o);
;                 gv[q] = *(const u32x2*)(vb + row * 512 + h * 64 + q4 * 16 + (lj & 3) * 4);
;             }
;         }
;     };
;     auto up4 = [](const u32x2 x) { return (f32x4){bf_lo(x.x), bf_hi(x.x), bf_lo(x.y), bf_hi(x.y)}; };
;     float selv[16];
; #pragma unroll
;     for (int i = 0; i < 16; ++i) selv[i] = (seg == i) ? 1.0f : 0.0f;
;     const int nch = T / 32;
;     gload(0);
; #pragma unroll 1
;     for (int c = 0; c < nch; ++c) {
;         LAS unsigned char* b = lds + (c & 1) * BUF;
;         if (ldr) {
; #pragma unroll
;             for (int q = 0; q < 2; ++q) {
;                 const int st_ = lstep + q * 16;
;                 *(LAS f32x4*)(b + st_ * 256 + lj * 16) = gd[q];
;                 *(LAS f32x4*)(b + 8192 + st_ * 256 + lj * 16) = up4(gk[q]);
;                 *(LAS f32x4*)(b + 16384 + st_ * 256 + lj * 16) = up4(ga[q]);
.LBB0_757:
	v_lshrrev_b32_e32 v2, 6, v200
	s_and_b32 s47, s44, 7
	s_lshr_b32 s5, s44, 3
	s_lshl_b32 s47, s47, 3
	s_lshr_b32 s4, s5, 2
	s_add_i32 s47, s47, s4
	s_lshl_b32 s47, s47, 2
	s_and_b32 s5, s5, 3
	s_or_b32 s47, s47, s5
	s_bfe_u32 s45, s47, 0x30002
	s_ashr_i32 s33, s47, 5
	v_readfirstlane_b32 s46, v2
	s_lshl_b32 s42, s33, 12
	s_lshl_b32 s4, s47, 4
	s_and_b32 s43, s4, 48
	s_waitcnt vmcnt(0)
	s_mov_b32 s22, 0
	s_mov_b32 s38, 35328
	s_mov_b32 s39, 0xffff7600
	v_and_b32_e32 v0, 63, v200
	s_cmp_lt_i32 s46, 4
	s_cbranch_scc0 .Lrw3_loader
	s_mov_b32 s98, 0xcccccccc
	s_mov_b32 s99, 0xcccccccc
	s_mov_b32 s100, 0xaaaaaaaa
	s_mov_b32 s101, 0xaaaaaaaa
	v_and_b32_e32 v196, 15, v0
	v_lshrrev_b32_e32 v194, 4, v0
	s_lshl_b32 s4, s46, 2
	v_add_u32_e32 v194, s4, v194
	v_lshlrev_b32_e32 v2, 4, v196
	v_mul_u32_u24_e32 v3, 144, v194
	v_add_u32_e32 v3, 32768, v3
	v_add_u32_e32 v4, 35072, v2
	v_add_u32_e32 v5, s42, v196
	v_add_u32_e32 v194, s43, v194
	s_lshl_b32 s4, s45, 7
	s_add_u32 s4, s18, s4
	s_addc_u32 s5, s19, 0
	v_lshlrev_b32_e32 v198, 1, v194
	v_mov_b32_e32 v199, 0
	v_lshl_add_u64 v[6:7], s[4:5], 0, v[198:199]
	s_lshl_b32 s4, s33, 3
	s_or_b32 s4, s4, s45
	s_lshl_b32 s4, s4, 14
	s_add_u32 s4, s15, s4
	s_addc_u32 s5, s35, 0
	v_lshlrev_b32_e32 v198, 8, v194
	v_lshl_add_u32 v198, v196, 4, v198
	v_lshl_add_u64 v[8:9], s[4:5], 0, v[198:199]
	v_mov_b32_e32 v12, 0
	v_mov_b32_e32 v13, 0
	v_mov_b32_e32 v14, 0
	v_mov_b32_e32 v15, 0
.Lrw3_cloop:
	s_barrier
	ds_read_b128 v[76:79], v2 offset:0
	ds_read_b128 v[84:87], v2 offset:16384
	ds_read_b128 v[80:83], v2 offset:8192
	ds_read_b128 v[124:127], v2 offset:24576
	ds_read_b128 v[24:27], v3 offset:0
	ds_read_b128 v[88:91], v2 offset:256
	ds_read_b128 v[96:99], v2 offset:16640
	ds_read_b128 v[92:95], v2 offset:8448
	ds_read_b128 v[128:131], v2 offset:24832
	ds_read_b128 v[100:103], v2 offset:512
	ds_read_b128 v[108:111], v2 offset:16896
	ds_read_b128 v[104:107], v2 offset:8704
	ds_read_b128 v[132:135], v2 offset:25088
	s_waitcnt lgkmcnt(8)
	v_pk_mul_f32 v[72:73], v[12:13], v[76:77]
	v_pk_fma_f32 v[72:73], v[14:15], v[78:79], v[72:73]
	ds_read_b128 v[112:115], v2 offset:768
	v_add_f32_e32 v74, v72, v73
	ds_read_b128 v[120:123], v2 offset:17152
	ds_read_b128 v[116:119], v2 offset:8960
	v_add_f32_dpp v74, v74, v74 quad_perm:[1,0,3,2] row_mask:0xf bank_mask:0xf bound_ctrl:1
	ds_read_b128 v[136:139], v2 offset:25344
	v_pk_fma_f32 v[16:17], v[24:25], v[84:85], v[12:13] op_sel_hi:[0,1,1]
	v_add_f32_dpp v74, v74, v74 quad_perm:[2,3,0,1] row_mask:0xf bank_mask:0xf bound_ctrl:1
	v_pk_fma_f32 v[18:19], v[24:25], v[86:87], v[14:15] op_sel_hi:[0,1,1]
	s_nop 0
	v_add_f32_dpp v74, v74, v74 row_half_mirror row_mask:0xf bank_mask:0xf bound_ctrl:1
	s_nop 1
	v_add_f32_dpp v74, v74, v74 row_mirror row_mask:0xf bank_mask:0xf bound_ctrl:1
	v_pk_fma_f32 v[12:13], v[80:81], v[74:75], v[16:17] op_sel_hi:[1,0,1] neg_lo:[0,1,0] neg_hi:[0,1,0]
	v_pk_fma_f32 v[14:15], v[82:83], v[74:75], v[18:19] op_sel_hi:[1,0,1] neg_lo:[0,1,0] neg_hi:[0,1,0]
	s_waitcnt lgkmcnt(8)
	v_pk_mul_f32 v[72:73], v[12:13], v[88:89]
	v_pk_fma_f32 v[72:73], v[14:15], v[90:91], v[72:73]
	ds_read_b128 v[76:79], v2 offset:1024
	v_add_f32_e32 v74, v72, v73
	ds_read_b128 v[84:87], v2 offset:17408
	ds_read_b128 v[80:83], v2 offset:9216
	v_add_f32_dpp v74, v74, v74 quad_perm:[1,0,3,2] row_mask:0xf bank_mask:0xf bound_ctrl:1
	ds_read_b128 v[140:143], v2 offset:25600
	ds_read_b128 v[28:31], v3 offset:16
	v_add_f32_dpp v74, v74, v74 quad_perm:[2,3,0,1] row_mask:0xf bank_mask:0xf bound_ctrl:1
	v_pk_fma_f32 v[16:17], v[24:25], v[96:97], v[12:13] op_sel:[1,0,0] op_sel_hi:[1,1,1]
	v_pk_fma_f32 v[18:19], v[24:25], v[98:99], v[14:15] op_sel:[1,0,0] op_sel_hi:[1,1,1]
	v_add_f32_dpp v74, v74, v74 row_half_mirror row_mask:0xf bank_mask:0xf bound_ctrl:1
	v_pk_mul_f32 v[198:199], v[12:13], v[124:125]
	v_pk_fma_f32 v[198:199], v[14:15], v[126:127], v[198:199]
	v_add_f32_dpp v74, v74, v74 row_mirror row_mask:0xf bank_mask:0xf bound_ctrl:1
	v_add_f32_e32 v144, v198, v199
	v_pk_fma_f32 v[12:13], v[92:93], v[74:75], v[16:17] op_sel_hi:[1,0,1] neg_lo:[0,1,0] neg_hi:[0,1,0]
	v_pk_fma_f32 v[14:15], v[94:95], v[74:75], v[18:19] op_sel_hi:[1,0,1] neg_lo:[0,1,0] neg_hi:[0,1,0]
	s_waitcnt lgkmcnt(9)
	v_pk_mul_f32 v[72:73], v[12:13], v[100:101]
	v_pk_fma_f32 v[72:73], v[14:15], v[102:103], v[72:73]
	ds_read_b128 v[88:91], v2 offset:1280
	v_add_f32_e32 v74, v72, v73
	ds_read_b128 v[96:99], v2 offset:17664
	ds_read_b128 v[92:95], v2 offset:9472
	v_add_f32_dpp v74, v74, v74 quad_perm:[1,0,3,2] row_mask:0xf bank_mask:0xf bound_ctrl:1
	ds_read_b128 v[124:127], v2 offset:25856
	v_pk_fma_f32 v[16:17], v[26:27], v[108:109], v[12:13] op_sel_hi:[0,1,1]
	v_add_f32_dpp v74, v74, v74 quad_perm:[2,3,0,1] row_mask:0xf bank_mask:0xf bound_ctrl:1
	v_pk_fma_f32 v[18:19], v[26:27], v[110:111], v[14:15] op_sel_hi:[0,1,1]
	v_pk_mul_f32 v[198:199], v[12:13], v[128:129]
	v_add_f32_dpp v74, v74, v74 row_half_mirror row_mask:0xf bank_mask:0xf bound_ctrl:1
	v_pk_fma_f32 v[198:199], v[14:15], v[130:131], v[198:199]
	v_add_f32_e32 v145, v198, v199
	v_add_f32_dpp v74, v74, v74 row_mirror row_mask:0xf bank_mask:0xf bound_ctrl:1
	v_pk_fma_f32 v[12:13], v[104:105], v[74:75], v[16:17] op_sel_hi:[1,0,1] neg_lo:[0,1,0] neg_hi:[0,1,0]
	v_pk_fma_f32 v[14:15], v[106:107], v[74:75], v[18:19] op_sel_hi:[1,0,1] neg_lo:[0,1,0] neg_hi:[0,1,0]
	s_waitcnt lgkmcnt(9)
; #define LAS __attribute__((address_space(3)))
; __device__ __forceinline__ bf16_t f2bf(float f) { return (bf16_t)(cvt_pk_bf16(f, 0.f) & 0xffffu); }
; #define RW_LD(X, s) do { X.d = *(const LAS f32x4*)(bs + (s) * 256); X.k = *(const LAS f32x4*)(bs + 8192 + (s) * 256); X.a = *(const LAS f32x4*)(bs + 16384 + (s) * 256); \
;                          X.p = *(const LAS f32x4*)(bs + 24576 + (s) * 256); X.r = *(const LAS f32x4*)(bs + 32768 + (s) * 256); X.v = *(const LAS float*)(bv + (s) * 64); } while (0)
; #define RW_STEP(X, s) do { float sa = fmaf(S[3], X.k[3], fmaf(S[2], X.k[2], fmaf(S[1], X.k[1], S[0] * X.k[0]))); const f32x4 T = S * X.d + X.v * X.p; sa = -red16(sa); \
;                            S = T + sa * X.a; float y = fmaf(S[3], X.r[3], fmaf(S[2], X.r[2], fmaf(S[1], X.r[1], S[0] * X.r[0]))); y = red16(y); \
;                            yk = fmaf(selv[(s) & 15], y, yk); } while (0)
; #define RW_YST(s) do { if ((s) == 15) { ob[(size_t)(rowbase + c * 32 + seg) * D + 512 + h * 64 + vrow] = f2bf(yk); yk = 0.f; } } while (0)
; __device__ __forceinline__ void rwkv_scan(const Params& p, LAS unsigned char* lds, int rowbase, int T, int h, int q4, const float* S0, float* Sout) {
;     ...
;         if (comp) {
;             const LAS unsigned char* bs = b + seg * 16; const LAS unsigned char* bv = b + 40960 + vloc * 4;
;     ...
;             RwStep xa, xb, xc; float yk = 0.f;
;     ...
;             RW_LD(xa, 0); RW_LD(xb, 1);
; #pragma unroll
;             for (int s = 0; s < 30; s += 3) {
;                 RW_LD(xc, s + 2); RW_STEP(xa, s); RW_YST(s);
;                 RW_LD(xa, s + 3); RW_STEP(xb, s + 1); RW_YST(s + 1);
;                 RW_LD(xb, s + 4); RW_STEP(xc, s + 2); RW_YST(s + 2);
;             }
;             RW_STEP(xa, 30); RW_STEP(xb, 31);
;             ob[(size_t)(rowbase + c * 32 + 16 + seg) * D + 512 + h * 64 + vrow] = f2bf(yk);
	v_pk_mul_f32 v[72:73], v[12:13], v[112:113]
	v_pk_fma_f32 v[72:73], v[14:15], v[114:115], v[72:73]
	ds_read_b128 v[100:103], v2 offset:1536
	v_add_f32_e32 v74, v72, v73
	ds_read_b128 v[108:111], v2 offset:17920
	ds_read_b128 v[104:107], v2 offset:9728
	v_add_f32_dpp v74, v74, v74 quad_perm:[1,0,3,2] row_mask:0xf bank_mask:0xf bound_ctrl:1
	ds_read_b128 v[128:131], v2 offset:26112
	v_pk_fma_f32 v[16:17], v[26:27], v[120:121], v[12:13] op_sel:[1,0,0] op_sel_hi:[1,1,1]
	v_add_f32_dpp v74, v74, v74 quad_perm:[2,3,0,1] row_mask:0xf bank_mask:0xf bound_ctrl:1
	v_pk_fma_f32 v[18:19], v[26:27], v[122:123], v[14:15] op_sel:[1,0,0] op_sel_hi:[1,1,1]
	v_pk_mul_f32 v[198:199], v[12:13], v[132:133]
	v_add_f32_dpp v74, v74, v74 row_half_mirror row_mask:0xf bank_mask:0xf bound_ctrl:1
	v_pk_fma_f32 v[198:199], v[14:15], v[134:135], v[198:199]
	v_add_f32_e32 v146, v198, v199
	v_add_f32_dpp v74, v74, v74 row_mirror row_mask:0xf bank_mask:0xf bound_ctrl:1
	v_pk_fma_f32 v[12:13], v[116:117], v[74:75], v[16:17] op_sel_hi:[1,0,1] neg_lo:[0,1,0] neg_hi:[0,1,0]
	v_pk_fma_f32 v[14:15], v[118:119], v[74:75], v[18:19] op_sel_hi:[1,0,1] neg_lo:[0,1,0] neg_hi:[0,1,0]
	s_waitcnt lgkmcnt(8)
	v_pk_mul_f32 v[72:73], v[12:13], v[76:77]
	v_pk_fma_f32 v[72:73], v[14:15], v[78:79], v[72:73]
	ds_read_b128 v[112:115], v2 offset:1792
	v_add_f32_e32 v74, v72, v73
	ds_read_b128 v[120:123], v2 offset:18176
	ds_read_b128 v[116:119], v2 offset:9984
	v_add_f32_dpp v74, v74, v74 quad_perm:[1,0,3,2] row_mask:0xf bank_mask:0xf bound_ctrl:1
	ds_read_b128 v[132:135], v2 offset:26368
	v_pk_fma_f32 v[16:17], v[28:29], v[84:85], v[12:13] op_sel_hi:[0,1,1]
	v_add_f32_dpp v74, v74, v74 quad_perm:[2,3,0,1] row_mask:0xf bank_mask:0xf bound_ctrl:1
	v_pk_fma_f32 v[18:19], v[28:29], v[86:87], v[14:15] op_sel_hi:[0,1,1]
	v_pk_mul_f32 v[198:199], v[12:13], v[136:137]
	v_add_f32_dpp v74, v74, v74 row_half_mirror row_mask:0xf bank_mask:0xf bound_ctrl:1
	v_pk_fma_f32 v[198:199], v[14:15], v[138:139], v[198:199]
	v_add_f32_e32 v147, v198, v199
	v_add_f32_dpp v74, v74, v74 row_mirror row_mask:0xf bank_mask:0xf bound_ctrl:1
	v_pk_fma_f32 v[12:13], v[80:81], v[74:75], v[16:17] op_sel_hi:[1,0,1] neg_lo:[0,1,0] neg_hi:[0,1,0]
	v_pk_fma_f32 v[14:15], v[82:83], v[74:75], v[18:19] op_sel_hi:[1,0,1] neg_lo:[0,1,0] neg_hi:[0,1,0]
	s_waitcnt lgkmcnt(8)
	v_pk_mul_f32 v[72:73], v[12:13], v[88:89]
	v_pk_fma_f32 v[72:73], v[14:15], v[90:91], v[72:73]
	ds_read_b128 v[76:79], v2 offset:2048
	v_add_f32_e32 v74, v72, v73
	ds_read_b128 v[84:87], v2 offset:18432
	ds_read_b128 v[80:83], v2 offset:10240
	v_add_f32_dpp v74, v74, v74 quad_perm:[1,0,3,2] row_mask:0xf bank_mask:0xf bound_ctrl:1
	ds_read_b128 v[136:139], v2 offset:26624
	ds_read_b128 v[24:27], v3 offset:32
	v_add_f32_dpp v74, v74, v74 quad_perm:[2,3,0,1] row_mask:0xf bank_mask:0xf bound_ctrl:1
	v_pk_fma_f32 v[16:17], v[28:29], v[96:97], v[12:13] op_sel:[1,0,0] op_sel_hi:[1,1,1]
	v_pk_fma_f32 v[18:19], v[28:29], v[98:99], v[14:15] op_sel:[1,0,0] op_sel_hi:[1,1,1]
	v_add_f32_dpp v74, v74, v74 row_half_mirror row_mask:0xf bank_mask:0xf bound_ctrl:1
	v_pk_mul_f32 v[198:199], v[12:13], v[140:141]
	v_pk_fma_f32 v[198:199], v[14:15], v[142:143], v[198:199]
	v_add_f32_dpp v74, v74, v74 row_mirror row_mask:0xf bank_mask:0xf bound_ctrl:1
	v_add_f32_e32 v148, v198, v199
	v_pk_fma_f32 v[12:13], v[92:93], v[74:75], v[16:17] op_sel_hi:[1,0,1] neg_lo:[0,1,0] neg_hi:[0,1,0]
	v_pk_fma_f32 v[14:15], v[94:95], v[74:75], v[18:19] op_sel_hi:[1,0,1] neg_lo:[0,1,0] neg_hi:[0,1,0]
	s_waitcnt lgkmcnt(9)
	v_pk_mul_f32 v[72:73], v[12:13], v[100:101]
	v_pk_fma_f32 v[72:73], v[14:15], v[102:103], v[72:73]
	ds_read_b128 v[88:91], v2 offset:2304
	v_add_f32_e32 v74, v72, v73
	ds_read_b128 v[96:99], v2 offset:18688
	ds_read_b128 v[92:95], v2 offset:10496
	v_add_f32_dpp v74, v74, v74 quad_perm:[1,0,3,2] row_mask:0xf bank_mask:0xf bound_ctrl:1
	ds_read_b128 v[140:143], v2 offset:26880
	v_pk_fma_f32 v[16:17], v[30:31], v[108:109], v[12:13] op_sel_hi:[0,1,1]
	v_add_f32_dpp v74, v74, v74 quad_perm:[2,3,0,1] row_mask:0xf bank_mask:0xf bound_ctrl:1
	v_pk_fma_f32 v[18:19], v[30:31], v[110:111], v[14:15] op_sel_hi:[0,1,1]
	v_pk_mul_f32 v[198:199], v[12:13], v[124:125]
	v_add_f32_dpp v74, v74, v74 row_half_mirror row_mask:0xf bank_mask:0xf bound_ctrl:1
	v_pk_fma_f32 v[198:199], v[14:15], v[126:127], v[198:199]
	v_add_f32_e32 v149, v198, v199
	v_add_f32_dpp v74, v74, v74 row_mirror row_mask:0xf bank_mask:0xf bound_ctrl:1
	v_pk_fma_f32 v[12:13], v[104:105], v[74:75], v[16:17] op_sel_hi:[1,0,1] neg_lo:[0,1,0] neg_hi:[0,1,0]
	v_pk_fma_f32 v[14:15], v[106:107], v[74:75], v[18:19] op_sel_hi:[1,0,1] neg_lo:[0,1,0] neg_hi:[0,1,0]
	s_waitcnt lgkmcnt(9)
	v_pk_mul_f32 v[72:73], v[12:13], v[112:113]
	v_pk_fma_f32 v[72:73], v[14:15], v[114:115], v[72:73]
	ds_read_b128 v[100:103], v2 offset:2560
	v_add_f32_e32 v74, v72, v73
	ds_read_b128 v[108:111], v2 offset:18944
	ds_read_b128 v[104:107], v2 offset:10752
	v_add_f32_dpp v74, v74, v74 quad_perm:[1,0,3,2] row_mask:0xf bank_mask:0xf bound_ctrl:1
	ds_read_b128 v[124:127], v2 offset:27136
	v_pk_fma_f32 v[16:17], v[30:31], v[120:121], v[12:13] op_sel:[1,0,0] op_sel_hi:[1,1,1]
	v_add_f32_dpp v74, v74, v74 quad_perm:[2,3,0,1] row_mask:0xf bank_mask:0xf bound_ctrl:1
	v_pk_fma_f32 v[18:19], v[30:31], v[122:123], v[14:15] op_sel:[1,0,0] op_sel_hi:[1,1,1]
	v_pk_mul_f32 v[198:199], v[12:13], v[128:129]
	v_add_f32_dpp v74, v74, v74 row_half_mirror row_mask:0xf bank_mask:0xf bound_ctrl:1
	v_pk_fma_f32 v[198:199], v[14:15], v[130:131], v[198:199]
	v_add_f32_e32 v150, v198, v199
	v_add_f32_dpp v74, v74, v74 row_mirror row_mask:0xf bank_mask:0xf bound_ctrl:1
	v_pk_fma_f32 v[12:13], v[116:117], v[74:75], v[16:17] op_sel_hi:[1,0,1] neg_lo:[0,1,0] neg_hi:[0,1,0]
	v_pk_fma_f32 v[14:15], v[118:119], v[74:75], v[18:19] op_sel_hi:[1,0,1] neg_lo:[0,1,0] neg_hi:[0,1,0]
	s_waitcnt lgkmcnt(8)
; #define LAS __attribute__((address_space(3)))
; __device__ __forceinline__ bf16_t f2bf(float f) { return (bf16_t)(cvt_pk_bf16(f, 0.f) & 0xffffu); }
; #define RW_LD(X, s) do { X.d = *(const LAS f32x4*)(bs + (s) * 256); X.k = *(const LAS f32x4*)(bs + 8192 + (s) * 256); X.a = *(const LAS f32x4*)(bs + 16384 + (s) * 256); \
;                          X.p = *(const LAS f32x4*)(bs + 24576 + (s) * 256); X.r = *(const LAS f32x4*)(bs + 32768 + (s) * 256); X.v = *(const LAS float*)(bv + (s) * 64); } while (0)
; #define RW_STEP(X, s) do { float sa = fmaf(S[3], X.k[3], fmaf(S[2], X.k[2], fmaf(S[1], X.k[1], S[0] * X.k[0]))); const f32x4 T = S * X.d + X.v * X.p; sa = -red16(sa); \
;                            S = T + sa * X.a; float y = fmaf(S[3], X.r[3], fmaf(S[2], X.r[2], fmaf(S[1], X.r[1], S[0] * X.r[0]))); y = red16(y); \
;                            yk = fmaf(selv[(s) & 15], y, yk); } while (0)
; #define RW_YST(s) do { if ((s) == 15) { ob[(size_t)(rowbase + c * 32 + seg) * D + 512 + h * 64 + vrow] = f2bf(yk); yk = 0.f; } } while (0)
; __device__ __forceinline__ void rwkv_scan(const Params& p, LAS unsigned char* lds, int rowbase, int T, int h, int q4, const float* S0, float* Sout) {
;     ...
;         if (comp) {
;             const LAS unsigned char* bs = b + seg * 16; const LAS unsigned char* bv = b + 40960 + vloc * 4;
;     ...
;             RwStep xa, xb, xc; float yk = 0.f;
;     ...
;             RW_LD(xa, 0); RW_LD(xb, 1);
; #pragma unroll
;             for (int s = 0; s < 30; s += 3) {
;                 RW_LD(xc, s + 2); RW_STEP(xa, s); RW_YST(s);
;                 RW_LD(xa, s + 3); RW_STEP(xb, s + 1); RW_YST(s + 1);
;                 RW_LD(xb, s + 4); RW_STEP(xc, s + 2); RW_YST(s + 2);
;             }
;             RW_STEP(xa, 30); RW_STEP(xb, 31);
;             ob[(size_t)(rowbase + c * 32 + 16 + seg) * D + 512 + h * 64 + vrow] = f2bf(yk);
	v_pk_mul_f32 v[72:73], v[12:13], v[76:77]
	v_pk_fma_f32 v[72:73], v[14:15], v[78:79], v[72:73]
	ds_read_b128 v[112:115], v2 offset:2816
	v_add_f32_e32 v74, v72, v73
	ds_read_b128 v[120:123], v2 offset:19200
	ds_read_b128 v[116:119], v2 offset:11008
	v_add_f32_dpp v74, v74, v74 quad_perm:[1,0,3,2] row_mask:0xf bank_mask:0xf bound_ctrl:1
	ds_read_b128 v[128:131], v2 offset:27392
	v_pk_fma_f32 v[16:17], v[24:25], v[84:85], v[12:13] op_sel_hi:[0,1,1]
	v_add_f32_dpp v74, v74, v74 quad_perm:[2,3,0,1] row_mask:0xf bank_mask:0xf bound_ctrl:1
	v_pk_fma_f32 v[18:19], v[24:25], v[86:87], v[14:15] op_sel_hi:[0,1,1]
	v_pk_mul_f32 v[198:199], v[12:13], v[132:133]
	v_add_f32_dpp v74, v74, v74 row_half_mirror row_mask:0xf bank_mask:0xf bound_ctrl:1
	v_pk_fma_f32 v[198:199], v[14:15], v[134:135], v[198:199]
	v_add_f32_e32 v151, v198, v199
	v_add_f32_dpp v74, v74, v74 row_mirror row_mask:0xf bank_mask:0xf bound_ctrl:1
	v_pk_fma_f32 v[12:13], v[80:81], v[74:75], v[16:17] op_sel_hi:[1,0,1] neg_lo:[0,1,0] neg_hi:[0,1,0]
	v_pk_fma_f32 v[14:15], v[82:83], v[74:75], v[18:19] op_sel_hi:[1,0,1] neg_lo:[0,1,0] neg_hi:[0,1,0]
	s_waitcnt lgkmcnt(8)
	v_pk_mul_f32 v[72:73], v[12:13], v[88:89]
	v_pk_fma_f32 v[72:73], v[14:15], v[90:91], v[72:73]
	ds_read_b128 v[76:79], v2 offset:3072
	v_add_f32_e32 v74, v72, v73
	ds_read_b128 v[84:87], v2 offset:19456
	ds_read_b128 v[80:83], v2 offset:11264
	v_add_f32_dpp v74, v74, v74 quad_perm:[1,0,3,2] row_mask:0xf bank_mask:0xf bound_ctrl:1
	ds_read_b128 v[132:135], v2 offset:27648
	ds_read_b128 v[28:31], v3 offset:48
	v_add_f32_dpp v74, v74, v74 quad_perm:[2,3,0,1] row_mask:0xf bank_mask:0xf bound_ctrl:1
	v_pk_fma_f32 v[16:17], v[24:25], v[96:97], v[12:13] op_sel:[1,0,0] op_sel_hi:[1,1,1]
	v_pk_fma_f32 v[18:19], v[24:25], v[98:99], v[14:15] op_sel:[1,0,0] op_sel_hi:[1,1,1]
	v_add_f32_dpp v74, v74, v74 row_half_mirror row_mask:0xf bank_mask:0xf bound_ctrl:1
	v_pk_mul_f32 v[198:199], v[12:13], v[136:137]
	v_pk_fma_f32 v[198:199], v[14:15], v[138:139], v[198:199]
	v_add_f32_dpp v74, v74, v74 row_mirror row_mask:0xf bank_mask:0xf bound_ctrl:1
	v_add_f32_e32 v152, v198, v199
	v_pk_fma_f32 v[12:13], v[92:93], v[74:75], v[16:17] op_sel_hi:[1,0,1] neg_lo:[0,1,0] neg_hi:[0,1,0]
	v_pk_fma_f32 v[14:15], v[94:95], v[74:75], v[18:19] op_sel_hi:[1,0,1] neg_lo:[0,1,0] neg_hi:[0,1,0]
	v_add_f32_dpp v176, v144, v144 row_mirror row_mask:0xf bank_mask:0x3
	s_nop 1
	v_add_f32_dpp v176, v152, v152 row_mirror row_mask:0xf bank_mask:0xc
	s_waitcnt lgkmcnt(9)
	v_pk_mul_f32 v[72:73], v[12:13], v[100:101]
	v_pk_fma_f32 v[72:73], v[14:15], v[102:103], v[72:73]
	ds_read_b128 v[88:91], v2 offset:3328
	v_add_f32_e32 v74, v72, v73
	ds_read_b128 v[96:99], v2 offset:19712
	ds_read_b128 v[92:95], v2 offset:11520
	v_add_f32_dpp v74, v74, v74 quad_perm:[1,0,3,2] row_mask:0xf bank_mask:0xf bound_ctrl:1
	ds_read_b128 v[136:139], v2 offset:27904
	v_pk_fma_f32 v[16:17], v[26:27], v[108:109], v[12:13] op_sel_hi:[0,1,1]
	v_add_f32_dpp v74, v74, v74 quad_perm:[2,3,0,1] row_mask:0xf bank_mask:0xf bound_ctrl:1
	v_pk_fma_f32 v[18:19], v[26:27], v[110:111], v[14:15] op_sel_hi:[0,1,1]
	v_pk_mul_f32 v[198:199], v[12:13], v[140:141]
	v_add_f32_dpp v74, v74, v74 row_half_mirror row_mask:0xf bank_mask:0xf bound_ctrl:1
	v_pk_fma_f32 v[198:199], v[14:15], v[142:143], v[198:199]
	v_add_f32_e32 v153, v198, v199
	v_add_f32_dpp v74, v74, v74 row_mirror row_mask:0xf bank_mask:0xf bound_ctrl:1
	v_pk_fma_f32 v[12:13], v[104:105], v[74:75], v[16:17] op_sel_hi:[1,0,1] neg_lo:[0,1,0] neg_hi:[0,1,0]
	v_pk_fma_f32 v[14:15], v[106:107], v[74:75], v[18:19] op_sel_hi:[1,0,1] neg_lo:[0,1,0] neg_hi:[0,1,0]
	v_add_f32_dpp v177, v145, v145 row_mirror row_mask:0xf bank_mask:0x3
	s_nop 1
	v_add_f32_dpp v177, v153, v153 row_mirror row_mask:0xf bank_mask:0xc
	s_waitcnt lgkmcnt(9)
	v_pk_mul_f32 v[72:73], v[12:13], v[112:113]
	v_pk_fma_f32 v[72:73], v[14:15], v[114:115], v[72:73]
	ds_read_b128 v[100:103], v2 offset:3584
	v_add_f32_e32 v74, v72, v73
	ds_read_b128 v[108:111], v2 offset:19968
	ds_read_b128 v[104:107], v2 offset:11776
	v_add_f32_dpp v74, v74, v74 quad_perm:[1,0,3,2] row_mask:0xf bank_mask:0xf bound_ctrl:1
	ds_read_b128 v[140:143], v2 offset:28160
	v_pk_fma_f32 v[16:17], v[26:27], v[120:121], v[12:13] op_sel:[1,0,0] op_sel_hi:[1,1,1]
	v_add_f32_dpp v74, v74, v74 quad_perm:[2,3,0,1] row_mask:0xf bank_mask:0xf bound_ctrl:1
	v_pk_fma_f32 v[18:19], v[26:27], v[122:123], v[14:15] op_sel:[1,0,0] op_sel_hi:[1,1,1]
	v_pk_mul_f32 v[198:199], v[12:13], v[124:125]
	v_add_f32_dpp v74, v74, v74 row_half_mirror row_mask:0xf bank_mask:0xf bound_ctrl:1
	v_pk_fma_f32 v[198:199], v[14:15], v[126:127], v[198:199]
	v_add_f32_e32 v154, v198, v199
	v_add_f32_dpp v74, v74, v74 row_mirror row_mask:0xf bank_mask:0xf bound_ctrl:1
	v_pk_fma_f32 v[12:13], v[116:117], v[74:75], v[16:17] op_sel_hi:[1,0,1] neg_lo:[0,1,0] neg_hi:[0,1,0]
	v_pk_fma_f32 v[14:15], v[118:119], v[74:75], v[18:19] op_sel_hi:[1,0,1] neg_lo:[0,1,0] neg_hi:[0,1,0]
	v_add_f32_dpp v178, v146, v146 row_mirror row_mask:0xf bank_mask:0x3
	s_nop 1
	v_add_f32_dpp v178, v154, v154 row_mirror row_mask:0xf bank_mask:0xc
	s_waitcnt lgkmcnt(8)
; #define LAS __attribute__((address_space(3)))
; __device__ __forceinline__ bf16_t f2bf(float f) { return (bf16_t)(cvt_pk_bf16(f, 0.f) & 0xffffu); }
; #define RW_LD(X, s) do { X.d = *(const LAS f32x4*)(bs + (s) * 256); X.k = *(const LAS f32x4*)(bs + 8192 + (s) * 256); X.a = *(const LAS f32x4*)(bs + 16384 + (s) * 256); \
;                          X.p = *(const LAS f32x4*)(bs + 24576 + (s) * 256); X.r = *(const LAS f32x4*)(bs + 32768 + (s) * 256); X.v = *(const LAS float*)(bv + (s) * 64); } while (0)
; #define RW_STEP(X, s) do { float sa = fmaf(S[3], X.k[3], fmaf(S[2], X.k[2], fmaf(S[1], X.k[1], S[0] * X.k[0]))); const f32x4 T = S * X.d + X.v * X.p; sa = -red16(sa); \
;                            S = T + sa * X.a; float y = fmaf(S[3], X.r[3], fmaf(S[2], X.r[2], fmaf(S[1], X.r[1], S[0] * X.r[0]))); y = red16(y); \
;                            yk = fmaf(selv[(s) & 15], y, yk); } while (0)
; #define RW_YST(s) do { if ((s) == 15) { ob[(size_t)(rowbase + c * 32 + seg) * D + 512 + h * 64 + vrow] = f2bf(yk); yk = 0.f; } } while (0)
; __device__ __forceinline__ void rwkv_scan(const Params& p, LAS unsigned char* lds, int rowbase, int T, int h, int q4, const float* S0, float* Sout) {
;     ...
;         if (comp) {
;             const LAS unsigned char* bs = b + seg * 16; const LAS unsigned char* bv = b + 40960 + vloc * 4;
;     ...
;             RwStep xa, xb, xc; float yk = 0.f;
;     ...
;             RW_LD(xa, 0); RW_LD(xb, 1);
; #pragma unroll
;             for (int s = 0; s < 30; s += 3) {
;                 RW_LD(xc, s + 2); RW_STEP(xa, s); RW_YST(s);
;                 RW_LD(xa, s + 3); RW_STEP(xb, s + 1); RW_YST(s + 1);
;                 RW_LD(xb, s + 4); RW_STEP(xc, s + 2); RW_YST(s + 2);
;             }
;             RW_STEP(xa, 30); RW_STEP(xb, 31);
;             ob[(size_t)(rowbase + c * 32 + 16 + seg) * D + 512 + h * 64 + vrow] = f2bf(yk);
	v_pk_mul_f32 v[72:73], v[12:13], v[76:77]
	v_pk_fma_f32 v[72:73], v[14:15], v[78:79], v[72:73]
	ds_read_b128 v[112:115], v2 offset:3840
	v_add_f32_e32 v74, v72, v73
	ds_read_b128 v[120:123], v2 offset:20224
	ds_read_b128 v[116:119], v2 offset:12032
	v_add_f32_dpp v74, v74, v74 quad_perm:[1,0,3,2] row_mask:0xf bank_mask:0xf bound_ctrl:1
	ds_read_b128 v[124:127], v2 offset:28416
	v_pk_fma_f32 v[16:17], v[28:29], v[84:85], v[12:13] op_sel_hi:[0,1,1]
	v_add_f32_dpp v74, v74, v74 quad_perm:[2,3,0,1] row_mask:0xf bank_mask:0xf bound_ctrl:1
	v_pk_fma_f32 v[18:19], v[28:29], v[86:87], v[14:15] op_sel_hi:[0,1,1]
	v_pk_mul_f32 v[198:199], v[12:13], v[128:129]
	v_add_f32_dpp v74, v74, v74 row_half_mirror row_mask:0xf bank_mask:0xf bound_ctrl:1
	v_pk_fma_f32 v[198:199], v[14:15], v[130:131], v[198:199]
	v_add_f32_e32 v155, v198, v199
	v_add_f32_dpp v74, v74, v74 row_mirror row_mask:0xf bank_mask:0xf bound_ctrl:1
	v_pk_fma_f32 v[12:13], v[80:81], v[74:75], v[16:17] op_sel_hi:[1,0,1] neg_lo:[0,1,0] neg_hi:[0,1,0]
	v_pk_fma_f32 v[14:15], v[82:83], v[74:75], v[18:19] op_sel_hi:[1,0,1] neg_lo:[0,1,0] neg_hi:[0,1,0]
	v_add_f32_dpp v179, v147, v147 row_mirror row_mask:0xf bank_mask:0x3
	s_nop 1
	v_add_f32_dpp v179, v155, v155 row_mirror row_mask:0xf bank_mask:0xc
	s_waitcnt lgkmcnt(8)
	v_pk_mul_f32 v[72:73], v[12:13], v[88:89]
	v_pk_fma_f32 v[72:73], v[14:15], v[90:91], v[72:73]
	ds_read_b128 v[76:79], v2 offset:4096
	v_add_f32_e32 v74, v72, v73
	ds_read_b128 v[84:87], v2 offset:20480
	ds_read_b128 v[80:83], v2 offset:12288
	v_add_f32_dpp v74, v74, v74 quad_perm:[1,0,3,2] row_mask:0xf bank_mask:0xf bound_ctrl:1
	ds_read_b128 v[128:131], v2 offset:28672
	ds_read_b128 v[24:27], v3 offset:64
	v_add_f32_dpp v74, v74, v74 quad_perm:[2,3,0,1] row_mask:0xf bank_mask:0xf bound_ctrl:1
	v_pk_fma_f32 v[16:17], v[28:29], v[96:97], v[12:13] op_sel:[1,0,0] op_sel_hi:[1,1,1]
	v_pk_fma_f32 v[18:19], v[28:29], v[98:99], v[14:15] op_sel:[1,0,0] op_sel_hi:[1,1,1]
	v_add_f32_dpp v74, v74, v74 row_half_mirror row_mask:0xf bank_mask:0xf bound_ctrl:1
	v_pk_mul_f32 v[198:199], v[12:13], v[132:133]
	v_pk_fma_f32 v[198:199], v[14:15], v[134:135], v[198:199]
	v_add_f32_dpp v74, v74, v74 row_mirror row_mask:0xf bank_mask:0xf bound_ctrl:1
	v_add_f32_e32 v156, v198, v199
	v_pk_fma_f32 v[12:13], v[92:93], v[74:75], v[16:17] op_sel_hi:[1,0,1] neg_lo:[0,1,0] neg_hi:[0,1,0]
	v_pk_fma_f32 v[14:15], v[94:95], v[74:75], v[18:19] op_sel_hi:[1,0,1] neg_lo:[0,1,0] neg_hi:[0,1,0]
	v_add_f32_dpp v180, v148, v148 row_mirror row_mask:0xf bank_mask:0x3
	s_nop 1
	v_add_f32_dpp v180, v156, v156 row_mirror row_mask:0xf bank_mask:0xc
	s_waitcnt lgkmcnt(9)
	v_pk_mul_f32 v[72:73], v[12:13], v[100:101]
	v_pk_fma_f32 v[72:73], v[14:15], v[102:103], v[72:73]
	ds_read_b128 v[88:91], v2 offset:4352
	v_add_f32_e32 v74, v72, v73
	ds_read_b128 v[96:99], v2 offset:20736
	ds_read_b128 v[92:95], v2 offset:12544
	v_add_f32_dpp v74, v74, v74 quad_perm:[1,0,3,2] row_mask:0xf bank_mask:0xf bound_ctrl:1
	ds_read_b128 v[132:135], v2 offset:28928
	v_pk_fma_f32 v[16:17], v[30:31], v[108:109], v[12:13] op_sel_hi:[0,1,1]
	v_add_f32_dpp v74, v74, v74 quad_perm:[2,3,0,1] row_mask:0xf bank_mask:0xf bound_ctrl:1
	v_pk_fma_f32 v[18:19], v[30:31], v[110:111], v[14:15] op_sel_hi:[0,1,1]
	v_pk_mul_f32 v[198:199], v[12:13], v[136:137]
	v_add_f32_dpp v74, v74, v74 row_half_mirror row_mask:0xf bank_mask:0xf bound_ctrl:1
	v_pk_fma_f32 v[198:199], v[14:15], v[138:139], v[198:199]
	v_add_f32_e32 v157, v198, v199
	v_add_f32_dpp v74, v74, v74 row_mirror row_mask:0xf bank_mask:0xf bound_ctrl:1
	v_pk_fma_f32 v[12:13], v[104:105], v[74:75], v[16:17] op_sel_hi:[1,0,1] neg_lo:[0,1,0] neg_hi:[0,1,0]
	v_pk_fma_f32 v[14:15], v[106:107], v[74:75], v[18:19] op_sel_hi:[1,0,1] neg_lo:[0,1,0] neg_hi:[0,1,0]
	v_add_f32_dpp v184, v176, v176 row_half_mirror row_mask:0xf bank_mask:0x5
	s_nop 1
	v_add_f32_dpp v184, v180, v180 row_half_mirror row_mask:0xf bank_mask:0xa
	s_waitcnt lgkmcnt(9)
	v_pk_mul_f32 v[72:73], v[12:13], v[112:113]
	v_pk_fma_f32 v[72:73], v[14:15], v[114:115], v[72:73]
	ds_read_b128 v[100:103], v2 offset:4608
	v_add_f32_e32 v74, v72, v73
	ds_read_b128 v[108:111], v2 offset:20992
	ds_read_b128 v[104:107], v2 offset:12800
	v_add_f32_dpp v74, v74, v74 quad_perm:[1,0,3,2] row_mask:0xf bank_mask:0xf bound_ctrl:1
	ds_read_b128 v[136:139], v2 offset:29184
	v_pk_fma_f32 v[16:17], v[30:31], v[120:121], v[12:13] op_sel:[1,0,0] op_sel_hi:[1,1,1]
	v_add_f32_dpp v74, v74, v74 quad_perm:[2,3,0,1] row_mask:0xf bank_mask:0xf bound_ctrl:1
	v_pk_fma_f32 v[18:19], v[30:31], v[122:123], v[14:15] op_sel:[1,0,0] op_sel_hi:[1,1,1]
	v_pk_mul_f32 v[198:199], v[12:13], v[140:141]
	v_add_f32_dpp v74, v74, v74 row_half_mirror row_mask:0xf bank_mask:0xf bound_ctrl:1
	v_pk_fma_f32 v[198:199], v[14:15], v[142:143], v[198:199]
	v_add_f32_e32 v158, v198, v199
	v_add_f32_dpp v74, v74, v74 row_mirror row_mask:0xf bank_mask:0xf bound_ctrl:1
	v_pk_fma_f32 v[12:13], v[116:117], v[74:75], v[16:17] op_sel_hi:[1,0,1] neg_lo:[0,1,0] neg_hi:[0,1,0]
	v_pk_fma_f32 v[14:15], v[118:119], v[74:75], v[18:19] op_sel_hi:[1,0,1] neg_lo:[0,1,0] neg_hi:[0,1,0]
	v_add_f32_dpp v181, v149, v149 row_mirror row_mask:0xf bank_mask:0x3
	s_nop 1
	v_add_f32_dpp v181, v157, v157 row_mirror row_mask:0xf bank_mask:0xc
	v_add_f32_dpp v185, v177, v177 row_half_mirror row_mask:0xf bank_mask:0x5
	s_waitcnt lgkmcnt(8)
; #define LAS __attribute__((address_space(3)))
; __device__ __forceinline__ bf16_t f2bf(float f) { return (bf16_t)(cvt_pk_bf16(f, 0.f) & 0xffffu); }
; #define RW_LD(X, s) do { X.d = *(const LAS f32x4*)(bs + (s) * 256); X.k = *(const LAS f32x4*)(bs + 8192 + (s) * 256); X.a = *(const LAS f32x4*)(bs + 16384 + (s) * 256); \
;                          X.p = *(const LAS f32x4*)(bs + 24576 + (s) * 256); X.r = *(const LAS f32x4*)(bs + 32768 + (s) * 256); X.v = *(const LAS float*)(bv + (s) * 64); } while (0)
; #define RW_STEP(X, s) do { float sa = fmaf(S[3], X.k[3], fmaf(S[2], X.k[2], fmaf(S[1], X.k[1], S[0] * X.k[0]))); const f32x4 T = S * X.d + X.v * X.p; sa = -red16(sa); \
;                            S = T + sa * X.a; float y = fmaf(S[3], X.r[3], fmaf(S[2], X.r[2], fmaf(S[1], X.r[1], S[0] * X.r[0]))); y = red16(y); \
;                            yk = fmaf(selv[(s) & 15], y, yk); } while (0)
; #define RW_YST(s) do { if ((s) == 15) { ob[(size_t)(rowbase + c * 32 + seg) * D + 512 + h * 64 + vrow] = f2bf(yk); yk = 0.f; } } while (0)
; __device__ __forceinline__ void rwkv_scan(const Params& p, LAS unsigned char* lds, int rowbase, int T, int h, int q4, const float* S0, float* Sout) {
;     ...
;         if (comp) {
;             const LAS unsigned char* bs = b + seg * 16; const LAS unsigned char* bv = b + 40960 + vloc * 4;
;     ...
;             RwStep xa, xb, xc; float yk = 0.f;
;     ...
;             RW_LD(xa, 0); RW_LD(xb, 1);
; #pragma unroll
;             for (int s = 0; s < 30; s += 3) {
;                 RW_LD(xc, s + 2); RW_STEP(xa, s); RW_YST(s);
;                 RW_LD(xa, s + 3); RW_STEP(xb, s + 1); RW_YST(s + 1);
;                 RW_LD(xb, s + 4); RW_STEP(xc, s + 2); RW_YST(s + 2);
;             }
;             RW_STEP(xa, 30); RW_STEP(xb, 31);
;             ob[(size_t)(rowbase + c * 32 + 16 + seg) * D + 512 + h * 64 + vrow] = f2bf(yk);
	v_pk_mul_f32 v[72:73], v[12:13], v[76:77]
	v_pk_fma_f32 v[72:73], v[14:15], v[78:79], v[72:73]
	ds_read_b128 v[112:115], v2 offset:4864
	v_add_f32_e32 v74, v72, v73
	ds_read_b128 v[120:123], v2 offset:21248
	ds_read_b128 v[116:119], v2 offset:13056
	v_add_f32_dpp v74, v74, v74 quad_perm:[1,0,3,2] row_mask:0xf bank_mask:0xf bound_ctrl:1
	ds_read_b128 v[140:143], v2 offset:29440
	v_pk_fma_f32 v[16:17], v[24:25], v[84:85], v[12:13] op_sel_hi:[0,1,1]
	v_add_f32_dpp v74, v74, v74 quad_perm:[2,3,0,1] row_mask:0xf bank_mask:0xf bound_ctrl:1
	v_pk_fma_f32 v[18:19], v[24:25], v[86:87], v[14:15] op_sel_hi:[0,1,1]
	v_pk_mul_f32 v[198:199], v[12:13], v[124:125]
	v_add_f32_dpp v74, v74, v74 row_half_mirror row_mask:0xf bank_mask:0xf bound_ctrl:1
	v_pk_fma_f32 v[198:199], v[14:15], v[126:127], v[198:199]
	v_add_f32_e32 v159, v198, v199
	v_add_f32_dpp v74, v74, v74 row_mirror row_mask:0xf bank_mask:0xf bound_ctrl:1
	v_pk_fma_f32 v[12:13], v[80:81], v[74:75], v[16:17] op_sel_hi:[1,0,1] neg_lo:[0,1,0] neg_hi:[0,1,0]
	v_pk_fma_f32 v[14:15], v[82:83], v[74:75], v[18:19] op_sel_hi:[1,0,1] neg_lo:[0,1,0] neg_hi:[0,1,0]
	v_add_f32_dpp v185, v181, v181 row_half_mirror row_mask:0xf bank_mask:0xa
	v_add_f32_dpp v182, v150, v150 row_mirror row_mask:0xf bank_mask:0x3
	s_nop 1
	v_add_f32_dpp v182, v158, v158 row_mirror row_mask:0xf bank_mask:0xc
	s_waitcnt lgkmcnt(8)
	v_pk_mul_f32 v[72:73], v[12:13], v[88:89]
	v_pk_fma_f32 v[72:73], v[14:15], v[90:91], v[72:73]
	ds_read_b128 v[76:79], v2 offset:5120
	v_add_f32_e32 v74, v72, v73
	ds_read_b128 v[84:87], v2 offset:21504
	ds_read_b128 v[80:83], v2 offset:13312
	v_add_f32_dpp v74, v74, v74 quad_perm:[1,0,3,2] row_mask:0xf bank_mask:0xf bound_ctrl:1
	ds_read_b128 v[124:127], v2 offset:29696
	ds_read_b128 v[28:31], v3 offset:80
	v_add_f32_dpp v74, v74, v74 quad_perm:[2,3,0,1] row_mask:0xf bank_mask:0xf bound_ctrl:1
	v_pk_fma_f32 v[16:17], v[24:25], v[96:97], v[12:13] op_sel:[1,0,0] op_sel_hi:[1,1,1]
	v_pk_fma_f32 v[18:19], v[24:25], v[98:99], v[14:15] op_sel:[1,0,0] op_sel_hi:[1,1,1]
	v_add_f32_dpp v74, v74, v74 row_half_mirror row_mask:0xf bank_mask:0xf bound_ctrl:1
	v_pk_mul_f32 v[198:199], v[12:13], v[128:129]
	v_pk_fma_f32 v[198:199], v[14:15], v[130:131], v[198:199]
	v_add_f32_dpp v74, v74, v74 row_mirror row_mask:0xf bank_mask:0xf bound_ctrl:1
	v_add_f32_e32 v160, v198, v199
	v_pk_fma_f32 v[12:13], v[92:93], v[74:75], v[16:17] op_sel_hi:[1,0,1] neg_lo:[0,1,0] neg_hi:[0,1,0]
	v_pk_fma_f32 v[14:15], v[94:95], v[74:75], v[18:19] op_sel_hi:[1,0,1] neg_lo:[0,1,0] neg_hi:[0,1,0]
	v_add_f32_dpp v186, v178, v178 row_half_mirror row_mask:0xf bank_mask:0x5
	s_nop 1
	v_add_f32_dpp v186, v182, v182 row_half_mirror row_mask:0xf bank_mask:0xa
	v_cndmask_b32_e64 v190, v184, v186, s[98:99]
	s_waitcnt lgkmcnt(9)
	v_pk_mul_f32 v[72:73], v[12:13], v[100:101]
	v_pk_fma_f32 v[72:73], v[14:15], v[102:103], v[72:73]
	ds_read_b128 v[88:91], v2 offset:5376
	v_add_f32_e32 v74, v72, v73
	ds_read_b128 v[96:99], v2 offset:21760
	ds_read_b128 v[92:95], v2 offset:13568
	v_add_f32_dpp v74, v74, v74 quad_perm:[1,0,3,2] row_mask:0xf bank_mask:0xf bound_ctrl:1
	ds_read_b128 v[128:131], v2 offset:29952
	v_pk_fma_f32 v[16:17], v[26:27], v[108:109], v[12:13] op_sel_hi:[0,1,1]
	v_add_f32_dpp v74, v74, v74 quad_perm:[2,3,0,1] row_mask:0xf bank_mask:0xf bound_ctrl:1
	v_pk_fma_f32 v[18:19], v[26:27], v[110:111], v[14:15] op_sel_hi:[0,1,1]
	v_pk_mul_f32 v[198:199], v[12:13], v[132:133]
	v_add_f32_dpp v74, v74, v74 row_half_mirror row_mask:0xf bank_mask:0xf bound_ctrl:1
	v_pk_fma_f32 v[198:199], v[14:15], v[134:135], v[198:199]
	v_add_f32_e32 v161, v198, v199
	v_add_f32_dpp v74, v74, v74 row_mirror row_mask:0xf bank_mask:0xf bound_ctrl:1
	v_pk_fma_f32 v[12:13], v[104:105], v[74:75], v[16:17] op_sel_hi:[1,0,1] neg_lo:[0,1,0] neg_hi:[0,1,0]
	v_pk_fma_f32 v[14:15], v[106:107], v[74:75], v[18:19] op_sel_hi:[1,0,1] neg_lo:[0,1,0] neg_hi:[0,1,0]
	v_cndmask_b32_e64 v191, v186, v184, s[98:99]
	s_nop 1
	v_add_f32_dpp v188, v191, v190 quad_perm:[2,3,0,1] row_mask:0xf bank_mask:0xf
	v_add_f32_dpp v183, v151, v151 row_mirror row_mask:0xf bank_mask:0x3
	s_waitcnt lgkmcnt(9)
	v_pk_mul_f32 v[72:73], v[12:13], v[112:113]
	v_pk_fma_f32 v[72:73], v[14:15], v[114:115], v[72:73]
	ds_read_b128 v[100:103], v2 offset:5632
	v_add_f32_e32 v74, v72, v73
	ds_read_b128 v[108:111], v2 offset:22016
	ds_read_b128 v[104:107], v2 offset:13824
	v_add_f32_dpp v74, v74, v74 quad_perm:[1,0,3,2] row_mask:0xf bank_mask:0xf bound_ctrl:1
	ds_read_b128 v[132:135], v2 offset:30208
	v_pk_fma_f32 v[16:17], v[26:27], v[120:121], v[12:13] op_sel:[1,0,0] op_sel_hi:[1,1,1]
	v_add_f32_dpp v74, v74, v74 quad_perm:[2,3,0,1] row_mask:0xf bank_mask:0xf bound_ctrl:1
	v_pk_fma_f32 v[18:19], v[26:27], v[122:123], v[14:15] op_sel:[1,0,0] op_sel_hi:[1,1,1]
	v_pk_mul_f32 v[198:199], v[12:13], v[136:137]
	v_add_f32_dpp v74, v74, v74 row_half_mirror row_mask:0xf bank_mask:0xf bound_ctrl:1
	v_pk_fma_f32 v[198:199], v[14:15], v[138:139], v[198:199]
	v_add_f32_e32 v162, v198, v199
	v_add_f32_dpp v74, v74, v74 row_mirror row_mask:0xf bank_mask:0xf bound_ctrl:1
	v_pk_fma_f32 v[12:13], v[116:117], v[74:75], v[16:17] op_sel_hi:[1,0,1] neg_lo:[0,1,0] neg_hi:[0,1,0]
	v_pk_fma_f32 v[14:15], v[118:119], v[74:75], v[18:19] op_sel_hi:[1,0,1] neg_lo:[0,1,0] neg_hi:[0,1,0]
	v_add_f32_dpp v183, v159, v159 row_mirror row_mask:0xf bank_mask:0xc
	v_add_f32_dpp v187, v179, v179 row_half_mirror row_mask:0xf bank_mask:0x5
	s_nop 1
	v_add_f32_dpp v187, v183, v183 row_half_mirror row_mask:0xf bank_mask:0xa
	s_waitcnt lgkmcnt(8)
; #define LAS __attribute__((address_space(3)))
; __device__ __forceinline__ bf16_t f2bf(float f) { return (bf16_t)(cvt_pk_bf16(f, 0.f) & 0xffffu); }
; #define RW_LD(X, s) do { X.d = *(const LAS f32x4*)(bs + (s) * 256); X.k = *(const LAS f32x4*)(bs + 8192 + (s) * 256); X.a = *(const LAS f32x4*)(bs + 16384 + (s) * 256); \
;                          X.p = *(const LAS f32x4*)(bs + 24576 + (s) * 256); X.r = *(const LAS f32x4*)(bs + 32768 + (s) * 256); X.v = *(const LAS float*)(bv + (s) * 64); } while (0)
; #define RW_STEP(X, s) do { float sa = fmaf(S[3], X.k[3], fmaf(S[2], X.k[2], fmaf(S[1], X.k[1], S[0] * X.k[0]))); const f32x4 T = S * X.d + X.v * X.p; sa = -red16(sa); \
;                            S = T + sa * X.a; float y = fmaf(S[3], X.r[3], fmaf(S[2], X.r[2], fmaf(S[1], X.r[1], S[0] * X.r[0]))); y = red16(y); \
;                            yk = fmaf(selv[(s) & 15], y, yk); } while (0)
; #define RW_YST(s) do { if ((s) == 15) { ob[(size_t)(rowbase + c * 32 + seg) * D + 512 + h * 64 + vrow] = f2bf(yk); yk = 0.f; } } while (0)
; __device__ __forceinline__ void rwkv_scan(const Params& p, LAS unsigned char* lds, int rowbase, int T, int h, int q4, const float* S0, float* Sout) {
;     ...
;         if (comp) {
;             const LAS unsigned char* bs = b + seg * 16; const LAS unsigned char* bv = b + 40960 + vloc * 4;
;     ...
;             RwStep xa, xb, xc; float yk = 0.f;
;     ...
;             RW_LD(xa, 0); RW_LD(xb, 1);
; #pragma unroll
;             for (int s = 0; s < 30; s += 3) {
;                 RW_LD(xc, s + 2); RW_STEP(xa, s); RW_YST(s);
;                 RW_LD(xa, s + 3); RW_STEP(xb, s + 1); RW_YST(s + 1);
;                 RW_LD(xb, s + 4); RW_STEP(xc, s + 2); RW_YST(s + 2);
;             }
;             RW_STEP(xa, 30); RW_STEP(xb, 31);
;             ob[(size_t)(rowbase + c * 32 + 16 + seg) * D + 512 + h * 64 + vrow] = f2bf(yk);
	v_pk_mul_f32 v[72:73], v[12:13], v[76:77]
	v_pk_fma_f32 v[72:73], v[14:15], v[78:79], v[72:73]
	ds_read_b128 v[112:115], v2 offset:5888
	v_add_f32_e32 v74, v72, v73
	ds_read_b128 v[120:123], v2 offset:22272
	ds_read_b128 v[116:119], v2 offset:14080
	v_add_f32_dpp v74, v74, v74 quad_perm:[1,0,3,2] row_mask:0xf bank_mask:0xf bound_ctrl:1
	ds_read_b128 v[136:139], v2 offset:30464
	v_pk_fma_f32 v[16:17], v[28:29], v[84:85], v[12:13] op_sel_hi:[0,1,1]
	v_add_f32_dpp v74, v74, v74 quad_perm:[2,3,0,1] row_mask:0xf bank_mask:0xf bound_ctrl:1
	v_pk_fma_f32 v[18:19], v[28:29], v[86:87], v[14:15] op_sel_hi:[0,1,1]
	v_pk_mul_f32 v[198:199], v[12:13], v[140:141]
	v_add_f32_dpp v74, v74, v74 row_half_mirror row_mask:0xf bank_mask:0xf bound_ctrl:1
	v_pk_fma_f32 v[198:199], v[14:15], v[142:143], v[198:199]
	v_add_f32_e32 v163, v198, v199
	v_add_f32_dpp v74, v74, v74 row_mirror row_mask:0xf bank_mask:0xf bound_ctrl:1
	v_pk_fma_f32 v[12:13], v[80:81], v[74:75], v[16:17] op_sel_hi:[1,0,1] neg_lo:[0,1,0] neg_hi:[0,1,0]
	v_pk_fma_f32 v[14:15], v[82:83], v[74:75], v[18:19] op_sel_hi:[1,0,1] neg_lo:[0,1,0] neg_hi:[0,1,0]
	v_cndmask_b32_e64 v190, v185, v187, s[98:99]
	v_cndmask_b32_e64 v191, v187, v185, s[98:99]
	s_nop 1
	v_add_f32_dpp v189, v191, v190 quad_perm:[2,3,0,1] row_mask:0xf bank_mask:0xf
	s_waitcnt lgkmcnt(8)
	v_pk_mul_f32 v[72:73], v[12:13], v[88:89]
	v_pk_fma_f32 v[72:73], v[14:15], v[90:91], v[72:73]
	ds_read_b128 v[76:79], v2 offset:6144
	v_add_f32_e32 v74, v72, v73
	ds_read_b128 v[84:87], v2 offset:22528
	ds_read_b128 v[80:83], v2 offset:14336
	v_add_f32_dpp v74, v74, v74 quad_perm:[1,0,3,2] row_mask:0xf bank_mask:0xf bound_ctrl:1
	ds_read_b128 v[140:143], v2 offset:30720
	ds_read_b128 v[24:27], v3 offset:96
	v_add_f32_dpp v74, v74, v74 quad_perm:[2,3,0,1] row_mask:0xf bank_mask:0xf bound_ctrl:1
	v_pk_fma_f32 v[16:17], v[28:29], v[96:97], v[12:13] op_sel:[1,0,0] op_sel_hi:[1,1,1]
	v_pk_fma_f32 v[18:19], v[28:29], v[98:99], v[14:15] op_sel:[1,0,0] op_sel_hi:[1,1,1]
	v_add_f32_dpp v74, v74, v74 row_half_mirror row_mask:0xf bank_mask:0xf bound_ctrl:1
	v_pk_mul_f32 v[198:199], v[12:13], v[124:125]
	v_pk_fma_f32 v[198:199], v[14:15], v[126:127], v[198:199]
	v_add_f32_dpp v74, v74, v74 row_mirror row_mask:0xf bank_mask:0xf bound_ctrl:1
	v_add_f32_e32 v164, v198, v199
	v_pk_fma_f32 v[12:13], v[92:93], v[74:75], v[16:17] op_sel_hi:[1,0,1] neg_lo:[0,1,0] neg_hi:[0,1,0]
	v_pk_fma_f32 v[14:15], v[94:95], v[74:75], v[18:19] op_sel_hi:[1,0,1] neg_lo:[0,1,0] neg_hi:[0,1,0]
	v_cndmask_b32_e64 v190, v188, v189, s[100:101]
	v_cndmask_b32_e64 v191, v189, v188, s[100:101]
	s_nop 1
	v_add_f32_dpp v192, v191, v190 quad_perm:[1,0,3,2] row_mask:0xf bank_mask:0xf
	s_waitcnt lgkmcnt(9)
	v_pk_mul_f32 v[72:73], v[12:13], v[100:101]
	v_pk_fma_f32 v[72:73], v[14:15], v[102:103], v[72:73]
	ds_read_b128 v[88:91], v2 offset:6400
	v_add_f32_e32 v74, v72, v73
	ds_read_b128 v[96:99], v2 offset:22784
	ds_read_b128 v[92:95], v2 offset:14592
	v_add_f32_dpp v74, v74, v74 quad_perm:[1,0,3,2] row_mask:0xf bank_mask:0xf bound_ctrl:1
	ds_read_b128 v[124:127], v2 offset:30976
	v_pk_fma_f32 v[16:17], v[30:31], v[108:109], v[12:13] op_sel_hi:[0,1,1]
	v_add_f32_dpp v74, v74, v74 quad_perm:[2,3,0,1] row_mask:0xf bank_mask:0xf bound_ctrl:1
	v_pk_fma_f32 v[18:19], v[30:31], v[110:111], v[14:15] op_sel_hi:[0,1,1]
	v_pk_mul_f32 v[198:199], v[12:13], v[128:129]
	v_add_f32_dpp v74, v74, v74 row_half_mirror row_mask:0xf bank_mask:0xf bound_ctrl:1
	v_pk_fma_f32 v[198:199], v[14:15], v[130:131], v[198:199]
	v_add_f32_e32 v165, v198, v199
	v_add_f32_dpp v74, v74, v74 row_mirror row_mask:0xf bank_mask:0xf bound_ctrl:1
	v_pk_fma_f32 v[12:13], v[104:105], v[74:75], v[16:17] op_sel_hi:[1,0,1] neg_lo:[0,1,0] neg_hi:[0,1,0]
	v_pk_fma_f32 v[14:15], v[106:107], v[74:75], v[18:19] op_sel_hi:[1,0,1] neg_lo:[0,1,0] neg_hi:[0,1,0]
	v_lshlrev_b32_e32 v194, 11, v5
	v_mov_b32_e32 v195, 0
	s_waitcnt lgkmcnt(9)
	v_pk_mul_f32 v[72:73], v[12:13], v[112:113]
	v_pk_fma_f32 v[72:73], v[14:15], v[114:115], v[72:73]
	ds_read_b128 v[100:103], v2 offset:6656
	v_add_f32_e32 v74, v72, v73
	ds_read_b128 v[108:111], v2 offset:23040
	ds_read_b128 v[104:107], v2 offset:14848
	v_add_f32_dpp v74, v74, v74 quad_perm:[1,0,3,2] row_mask:0xf bank_mask:0xf bound_ctrl:1
	ds_read_b128 v[128:131], v2 offset:31232
	v_pk_fma_f32 v[16:17], v[30:31], v[120:121], v[12:13] op_sel:[1,0,0] op_sel_hi:[1,1,1]
	v_add_f32_dpp v74, v74, v74 quad_perm:[2,3,0,1] row_mask:0xf bank_mask:0xf bound_ctrl:1
	v_pk_fma_f32 v[18:19], v[30:31], v[122:123], v[14:15] op_sel:[1,0,0] op_sel_hi:[1,1,1]
	v_pk_mul_f32 v[198:199], v[12:13], v[132:133]
	v_add_f32_dpp v74, v74, v74 row_half_mirror row_mask:0xf bank_mask:0xf bound_ctrl:1
	v_pk_fma_f32 v[198:199], v[14:15], v[134:135], v[198:199]
	v_add_f32_e32 v166, v198, v199
	v_add_f32_dpp v74, v74, v74 row_mirror row_mask:0xf bank_mask:0xf bound_ctrl:1
	v_pk_fma_f32 v[12:13], v[116:117], v[74:75], v[16:17] op_sel_hi:[1,0,1] neg_lo:[0,1,0] neg_hi:[0,1,0]
	v_pk_fma_f32 v[14:15], v[118:119], v[74:75], v[18:19] op_sel_hi:[1,0,1] neg_lo:[0,1,0] neg_hi:[0,1,0]
	v_cvt_pk_bf16_f32 v193, v192, v192
	v_lshl_add_u64 v[194:195], v[6:7], 0, v[194:195]
	s_waitcnt lgkmcnt(8)
; #define LAS __attribute__((address_space(3)))
; __device__ __forceinline__ bf16_t f2bf(float f) { return (bf16_t)(cvt_pk_bf16(f, 0.f) & 0xffffu); }
; #define RW_LD(X, s) do { X.d = *(const LAS f32x4*)(bs + (s) * 256); X.k = *(const LAS f32x4*)(bs + 8192 + (s) * 256); X.a = *(const LAS f32x4*)(bs + 16384 + (s) * 256); \
;                          X.p = *(const LAS f32x4*)(bs + 24576 + (s) * 256); X.r = *(const LAS f32x4*)(bs + 32768 + (s) * 256); X.v = *(const LAS float*)(bv + (s) * 64); } while (0)
; #define RW_STEP(X, s) do { float sa = fmaf(S[3], X.k[3], fmaf(S[2], X.k[2], fmaf(S[1], X.k[1], S[0] * X.k[0]))); const f32x4 T = S * X.d + X.v * X.p; sa = -red16(sa); \
;                            S = T + sa * X.a; float y = fmaf(S[3], X.r[3], fmaf(S[2], X.r[2], fmaf(S[1], X.r[1], S[0] * X.r[0]))); y = red16(y); \
;                            yk = fmaf(selv[(s) & 15], y, yk); } while (0)
; #define RW_YST(s) do { if ((s) == 15) { ob[(size_t)(rowbase + c * 32 + seg) * D + 512 + h * 64 + vrow] = f2bf(yk); yk = 0.f; } } while (0)
; __device__ __forceinline__ void rwkv_scan(const Params& p, LAS unsigned char* lds, int rowbase, int T, int h, int q4, const float* S0, float* Sout) {
;     ...
;         if (comp) {
;             const LAS unsigned char* bs = b + seg * 16; const LAS unsigned char* bv = b + 40960 + vloc * 4;
;     ...
;             RwStep xa, xb, xc; float yk = 0.f;
;     ...
;             RW_LD(xa, 0); RW_LD(xb, 1);
; #pragma unroll
;             for (int s = 0; s < 30; s += 3) {
;                 RW_LD(xc, s + 2); RW_STEP(xa, s); RW_YST(s);
;                 RW_LD(xa, s + 3); RW_STEP(xb, s + 1); RW_YST(s + 1);
;                 RW_LD(xb, s + 4); RW_STEP(xc, s + 2); RW_YST(s + 2);
;             }
;             RW_STEP(xa, 30); RW_STEP(xb, 31);
;             ob[(size_t)(rowbase + c * 32 + 16 + seg) * D + 512 + h * 64 + vrow] = f2bf(yk);
	v_pk_mul_f32 v[72:73], v[12:13], v[76:77]
	v_pk_fma_f32 v[72:73], v[14:15], v[78:79], v[72:73]
	ds_read_b128 v[112:115], v2 offset:6912
	v_add_f32_e32 v74, v72, v73
	ds_read_b128 v[120:123], v2 offset:23296
	ds_read_b128 v[116:119], v2 offset:15104
	v_add_f32_dpp v74, v74, v74 quad_perm:[1,0,3,2] row_mask:0xf bank_mask:0xf bound_ctrl:1
	ds_read_b128 v[132:135], v2 offset:31488
	v_pk_fma_f32 v[16:17], v[24:25], v[84:85], v[12:13] op_sel_hi:[0,1,1]
	v_add_f32_dpp v74, v74, v74 quad_perm:[2,3,0,1] row_mask:0xf bank_mask:0xf bound_ctrl:1
	v_pk_fma_f32 v[18:19], v[24:25], v[86:87], v[14:15] op_sel_hi:[0,1,1]
	v_pk_mul_f32 v[198:199], v[12:13], v[136:137]
	v_add_f32_dpp v74, v74, v74 row_half_mirror row_mask:0xf bank_mask:0xf bound_ctrl:1
	v_pk_fma_f32 v[198:199], v[14:15], v[138:139], v[198:199]
	v_add_f32_e32 v167, v198, v199
	v_add_f32_dpp v74, v74, v74 row_mirror row_mask:0xf bank_mask:0xf bound_ctrl:1
	v_pk_fma_f32 v[12:13], v[80:81], v[74:75], v[16:17] op_sel_hi:[1,0,1] neg_lo:[0,1,0] neg_hi:[0,1,0]
	v_pk_fma_f32 v[14:15], v[82:83], v[74:75], v[18:19] op_sel_hi:[1,0,1] neg_lo:[0,1,0] neg_hi:[0,1,0]
	global_store_short v[194:195], v193, off offset:1024
	s_waitcnt lgkmcnt(8)
	v_pk_mul_f32 v[72:73], v[12:13], v[88:89]
	v_pk_fma_f32 v[72:73], v[14:15], v[90:91], v[72:73]
	ds_read_b128 v[76:79], v2 offset:7168
	v_add_f32_e32 v74, v72, v73
	ds_read_b128 v[84:87], v2 offset:23552
	ds_read_b128 v[80:83], v2 offset:15360
	v_add_f32_dpp v74, v74, v74 quad_perm:[1,0,3,2] row_mask:0xf bank_mask:0xf bound_ctrl:1
	ds_read_b128 v[136:139], v2 offset:31744
	ds_read_b128 v[28:31], v3 offset:112
	v_add_f32_dpp v74, v74, v74 quad_perm:[2,3,0,1] row_mask:0xf bank_mask:0xf bound_ctrl:1
	v_pk_fma_f32 v[16:17], v[24:25], v[96:97], v[12:13] op_sel:[1,0,0] op_sel_hi:[1,1,1]
	v_pk_fma_f32 v[18:19], v[24:25], v[98:99], v[14:15] op_sel:[1,0,0] op_sel_hi:[1,1,1]
	v_add_f32_dpp v74, v74, v74 row_half_mirror row_mask:0xf bank_mask:0xf bound_ctrl:1
	v_pk_mul_f32 v[198:199], v[12:13], v[140:141]
	v_pk_fma_f32 v[198:199], v[14:15], v[142:143], v[198:199]
	v_add_f32_dpp v74, v74, v74 row_mirror row_mask:0xf bank_mask:0xf bound_ctrl:1
	v_add_f32_e32 v168, v198, v199
	v_pk_fma_f32 v[12:13], v[92:93], v[74:75], v[16:17] op_sel_hi:[1,0,1] neg_lo:[0,1,0] neg_hi:[0,1,0]
	v_pk_fma_f32 v[14:15], v[94:95], v[74:75], v[18:19] op_sel_hi:[1,0,1] neg_lo:[0,1,0] neg_hi:[0,1,0]
	v_add_f32_dpp v176, v160, v160 row_mirror row_mask:0xf bank_mask:0x3
	s_nop 1
	v_add_f32_dpp v176, v168, v168 row_mirror row_mask:0xf bank_mask:0xc
	s_waitcnt lgkmcnt(9)
	v_pk_mul_f32 v[72:73], v[12:13], v[100:101]
	v_pk_fma_f32 v[72:73], v[14:15], v[102:103], v[72:73]
	ds_read_b128 v[88:91], v2 offset:7424
	v_add_f32_e32 v74, v72, v73
	ds_read_b128 v[96:99], v2 offset:23808
	ds_read_b128 v[92:95], v2 offset:15616
	v_add_f32_dpp v74, v74, v74 quad_perm:[1,0,3,2] row_mask:0xf bank_mask:0xf bound_ctrl:1
	ds_read_b128 v[140:143], v2 offset:32000
	v_pk_fma_f32 v[16:17], v[26:27], v[108:109], v[12:13] op_sel_hi:[0,1,1]
	v_add_f32_dpp v74, v74, v74 quad_perm:[2,3,0,1] row_mask:0xf bank_mask:0xf bound_ctrl:1
	v_pk_fma_f32 v[18:19], v[26:27], v[110:111], v[14:15] op_sel_hi:[0,1,1]
	v_pk_mul_f32 v[198:199], v[12:13], v[124:125]
	v_add_f32_dpp v74, v74, v74 row_half_mirror row_mask:0xf bank_mask:0xf bound_ctrl:1
	v_pk_fma_f32 v[198:199], v[14:15], v[126:127], v[198:199]
	v_add_f32_e32 v169, v198, v199
	v_add_f32_dpp v74, v74, v74 row_mirror row_mask:0xf bank_mask:0xf bound_ctrl:1
	v_pk_fma_f32 v[12:13], v[104:105], v[74:75], v[16:17] op_sel_hi:[1,0,1] neg_lo:[0,1,0] neg_hi:[0,1,0]
	v_pk_fma_f32 v[14:15], v[106:107], v[74:75], v[18:19] op_sel_hi:[1,0,1] neg_lo:[0,1,0] neg_hi:[0,1,0]
	v_add_f32_dpp v177, v161, v161 row_mirror row_mask:0xf bank_mask:0x3
	s_nop 1
	v_add_f32_dpp v177, v169, v169 row_mirror row_mask:0xf bank_mask:0xc
	s_waitcnt lgkmcnt(9)
	v_pk_mul_f32 v[72:73], v[12:13], v[112:113]
	v_pk_fma_f32 v[72:73], v[14:15], v[114:115], v[72:73]
	ds_read_b128 v[100:103], v2 offset:7680
	v_add_f32_e32 v74, v72, v73
	ds_read_b128 v[108:111], v2 offset:24064
	ds_read_b128 v[104:107], v2 offset:15872
	v_add_f32_dpp v74, v74, v74 quad_perm:[1,0,3,2] row_mask:0xf bank_mask:0xf bound_ctrl:1
	ds_read_b128 v[124:127], v2 offset:32256
	v_pk_fma_f32 v[16:17], v[26:27], v[120:121], v[12:13] op_sel:[1,0,0] op_sel_hi:[1,1,1]
	v_add_f32_dpp v74, v74, v74 quad_perm:[2,3,0,1] row_mask:0xf bank_mask:0xf bound_ctrl:1
	v_pk_fma_f32 v[18:19], v[26:27], v[122:123], v[14:15] op_sel:[1,0,0] op_sel_hi:[1,1,1]
	v_pk_mul_f32 v[198:199], v[12:13], v[128:129]
	v_add_f32_dpp v74, v74, v74 row_half_mirror row_mask:0xf bank_mask:0xf bound_ctrl:1
	v_pk_fma_f32 v[198:199], v[14:15], v[130:131], v[198:199]
	v_add_f32_e32 v170, v198, v199
	v_add_f32_dpp v74, v74, v74 row_mirror row_mask:0xf bank_mask:0xf bound_ctrl:1
	v_pk_fma_f32 v[12:13], v[116:117], v[74:75], v[16:17] op_sel_hi:[1,0,1] neg_lo:[0,1,0] neg_hi:[0,1,0]
	v_pk_fma_f32 v[14:15], v[118:119], v[74:75], v[18:19] op_sel_hi:[1,0,1] neg_lo:[0,1,0] neg_hi:[0,1,0]
	v_add_f32_dpp v178, v162, v162 row_mirror row_mask:0xf bank_mask:0x3
	s_nop 1
	v_add_f32_dpp v178, v170, v170 row_mirror row_mask:0xf bank_mask:0xc
	s_waitcnt lgkmcnt(8)
; __device__ __forceinline__ bf16_t f2bf(float f) { return (bf16_t)(cvt_pk_bf16(f, 0.f) & 0xffffu); }
; #define RW_LD(X, s) do { X.d = *(const LAS f32x4*)(bs + (s) * 256); X.k = *(const LAS f32x4*)(bs + 8192 + (s) * 256); X.a = *(const LAS f32x4*)(bs + 16384 + (s) * 256); \
;                          X.p = *(const LAS f32x4*)(bs + 24576 + (s) * 256); X.r = *(const LAS f32x4*)(bs + 32768 + (s) * 256); X.v = *(const LAS float*)(bv + (s) * 64); } while (0)
; #define RW_STEP(X, s) do { float sa = fmaf(S[3], X.k[3], fmaf(S[2], X.k[2], fmaf(S[1], X.k[1], S[0] * X.k[0]))); const f32x4 T = S * X.d + X.v * X.p; sa = -red16(sa); \
;                            S = T + sa * X.a; float y = fmaf(S[3], X.r[3], fmaf(S[2], X.r[2], fmaf(S[1], X.r[1], S[0] * X.r[0]))); y = red16(y); \
;                            yk = fmaf(selv[(s) & 15], y, yk); } while (0)
; #define RW_YST(s) do { if ((s) == 15) { ob[(size_t)(rowbase + c * 32 + seg) * D + 512 + h * 64 + vrow] = f2bf(yk); yk = 0.f; } } while (0)
; __device__ __forceinline__ void rwkv_scan(const Params& p, LAS unsigned char* lds, int rowbase, int T, int h, int q4, const float* S0, float* Sout) {
;     ...
;             for (int s = 0; s < 30; s += 3) {
;                 RW_LD(xc, s + 2); RW_STEP(xa, s); RW_YST(s);
;                 RW_LD(xa, s + 3); RW_STEP(xb, s + 1); RW_YST(s + 1);
;                 RW_LD(xb, s + 4); RW_STEP(xc, s + 2); RW_YST(s + 2);
;             }
;             RW_STEP(xa, 30); RW_STEP(xb, 31);
;             ob[(size_t)(rowbase + c * 32 + 16 + seg) * D + 512 + h * 64 + vrow] = f2bf(yk);
;     ...
;         }
;     }
;     if (comp) *(f32x4*)(Sout + vrow * 64 + seg * 4) = S;
	v_pk_mul_f32 v[72:73], v[12:13], v[76:77]
	v_pk_fma_f32 v[72:73], v[14:15], v[78:79], v[72:73]
	ds_read_b128 v[112:115], v2 offset:7936
	v_add_f32_e32 v74, v72, v73
	ds_read_b128 v[120:123], v2 offset:24320
	ds_read_b128 v[116:119], v2 offset:16128
	v_add_f32_dpp v74, v74, v74 quad_perm:[1,0,3,2] row_mask:0xf bank_mask:0xf bound_ctrl:1
	ds_read_b128 v[128:131], v2 offset:32512
	v_pk_fma_f32 v[16:17], v[28:29], v[84:85], v[12:13] op_sel_hi:[0,1,1]
	v_add_f32_dpp v74, v74, v74 quad_perm:[2,3,0,1] row_mask:0xf bank_mask:0xf bound_ctrl:1
	v_pk_fma_f32 v[18:19], v[28:29], v[86:87], v[14:15] op_sel_hi:[0,1,1]
	v_pk_mul_f32 v[198:199], v[12:13], v[132:133]
	v_add_f32_dpp v74, v74, v74 row_half_mirror row_mask:0xf bank_mask:0xf bound_ctrl:1
	v_pk_fma_f32 v[198:199], v[14:15], v[134:135], v[198:199]
	v_add_f32_e32 v171, v198, v199
	v_add_f32_dpp v74, v74, v74 row_mirror row_mask:0xf bank_mask:0xf bound_ctrl:1
	v_pk_fma_f32 v[12:13], v[80:81], v[74:75], v[16:17] op_sel_hi:[1,0,1] neg_lo:[0,1,0] neg_hi:[0,1,0]
	v_pk_fma_f32 v[14:15], v[82:83], v[74:75], v[18:19] op_sel_hi:[1,0,1] neg_lo:[0,1,0] neg_hi:[0,1,0]
	v_add_f32_dpp v179, v163, v163 row_mirror row_mask:0xf bank_mask:0x3
	s_nop 1
	v_add_f32_dpp v179, v171, v171 row_mirror row_mask:0xf bank_mask:0xc
	s_waitcnt lgkmcnt(8)
	v_pk_mul_f32 v[72:73], v[12:13], v[88:89]
	v_pk_fma_f32 v[72:73], v[14:15], v[90:91], v[72:73]
	v_pk_fma_f32 v[16:17], v[28:29], v[96:97], v[12:13] op_sel:[1,0,0] op_sel_hi:[1,1,1]
	v_add_f32_e32 v74, v72, v73
	v_pk_fma_f32 v[18:19], v[28:29], v[98:99], v[14:15] op_sel:[1,0,0] op_sel_hi:[1,1,1]
	v_pk_mul_f32 v[198:199], v[12:13], v[136:137]
	v_add_f32_dpp v74, v74, v74 quad_perm:[1,0,3,2] row_mask:0xf bank_mask:0xf bound_ctrl:1
	v_pk_fma_f32 v[198:199], v[14:15], v[138:139], v[198:199]
	v_add_f32_e32 v172, v198, v199
	v_add_f32_dpp v74, v74, v74 quad_perm:[2,3,0,1] row_mask:0xf bank_mask:0xf bound_ctrl:1
	v_add_f32_dpp v180, v164, v164 row_mirror row_mask:0xf bank_mask:0x3
	s_nop 1
	v_add_f32_dpp v180, v172, v172 row_mirror row_mask:0xf bank_mask:0xc
	v_add_f32_dpp v74, v74, v74 row_half_mirror row_mask:0xf bank_mask:0xf bound_ctrl:1
	s_nop 1
	v_add_f32_dpp v74, v74, v74 row_mirror row_mask:0xf bank_mask:0xf bound_ctrl:1
	v_pk_fma_f32 v[12:13], v[92:93], v[74:75], v[16:17] op_sel_hi:[1,0,1] neg_lo:[0,1,0] neg_hi:[0,1,0]
	v_pk_fma_f32 v[14:15], v[94:95], v[74:75], v[18:19] op_sel_hi:[1,0,1] neg_lo:[0,1,0] neg_hi:[0,1,0]
	s_waitcnt lgkmcnt(4)
	v_pk_mul_f32 v[72:73], v[12:13], v[100:101]
	v_pk_fma_f32 v[72:73], v[14:15], v[102:103], v[72:73]
	v_pk_fma_f32 v[16:17], v[30:31], v[108:109], v[12:13] op_sel_hi:[0,1,1]
	v_add_f32_e32 v74, v72, v73
	v_pk_fma_f32 v[18:19], v[30:31], v[110:111], v[14:15] op_sel_hi:[0,1,1]
	v_pk_mul_f32 v[198:199], v[12:13], v[140:141]
	v_add_f32_dpp v74, v74, v74 quad_perm:[1,0,3,2] row_mask:0xf bank_mask:0xf bound_ctrl:1
	v_pk_fma_f32 v[198:199], v[14:15], v[142:143], v[198:199]
	v_add_f32_e32 v173, v198, v199
	v_add_f32_dpp v74, v74, v74 quad_perm:[2,3,0,1] row_mask:0xf bank_mask:0xf bound_ctrl:1
	v_add_f32_dpp v184, v176, v176 row_half_mirror row_mask:0xf bank_mask:0x5
	s_nop 1
	v_add_f32_dpp v184, v180, v180 row_half_mirror row_mask:0xf bank_mask:0xa
	v_add_f32_dpp v74, v74, v74 row_half_mirror row_mask:0xf bank_mask:0xf bound_ctrl:1
	s_nop 1
	v_add_f32_dpp v74, v74, v74 row_mirror row_mask:0xf bank_mask:0xf bound_ctrl:1
	v_pk_fma_f32 v[12:13], v[104:105], v[74:75], v[16:17] op_sel_hi:[1,0,1] neg_lo:[0,1,0] neg_hi:[0,1,0]
	v_pk_fma_f32 v[14:15], v[106:107], v[74:75], v[18:19] op_sel_hi:[1,0,1] neg_lo:[0,1,0] neg_hi:[0,1,0]
	s_waitcnt lgkmcnt(0)
	v_pk_mul_f32 v[72:73], v[12:13], v[112:113]
	v_pk_fma_f32 v[72:73], v[14:15], v[114:115], v[72:73]
	v_pk_fma_f32 v[16:17], v[30:31], v[120:121], v[12:13] op_sel:[1,0,0] op_sel_hi:[1,1,1]
	v_add_f32_e32 v74, v72, v73
	v_pk_fma_f32 v[18:19], v[30:31], v[122:123], v[14:15] op_sel:[1,0,0] op_sel_hi:[1,1,1]
	v_pk_mul_f32 v[198:199], v[12:13], v[124:125]
	v_add_f32_dpp v74, v74, v74 quad_perm:[1,0,3,2] row_mask:0xf bank_mask:0xf bound_ctrl:1
	v_pk_fma_f32 v[198:199], v[14:15], v[126:127], v[198:199]
	v_add_f32_e32 v174, v198, v199
	v_add_f32_dpp v74, v74, v74 quad_perm:[2,3,0,1] row_mask:0xf bank_mask:0xf bound_ctrl:1
	v_add_f32_dpp v181, v165, v165 row_mirror row_mask:0xf bank_mask:0x3
	s_nop 1
	v_add_f32_dpp v181, v173, v173 row_mirror row_mask:0xf bank_mask:0xc
	v_add_f32_dpp v74, v74, v74 row_half_mirror row_mask:0xf bank_mask:0xf bound_ctrl:1
	v_add_f32_dpp v185, v177, v177 row_half_mirror row_mask:0xf bank_mask:0x5
	s_nop 0
	v_add_f32_dpp v74, v74, v74 row_mirror row_mask:0xf bank_mask:0xf bound_ctrl:1
	v_pk_fma_f32 v[12:13], v[116:117], v[74:75], v[16:17] op_sel_hi:[1,0,1] neg_lo:[0,1,0] neg_hi:[0,1,0]
	v_pk_fma_f32 v[14:15], v[118:119], v[74:75], v[18:19] op_sel_hi:[1,0,1] neg_lo:[0,1,0] neg_hi:[0,1,0]
	ds_read_b128 v[20:23], v4
	v_pk_mul_f32 v[198:199], v[12:13], v[128:129]
	v_pk_fma_f32 v[198:199], v[14:15], v[130:131], v[198:199]
	v_add_f32_e32 v175, v198, v199
	v_add_f32_dpp v185, v181, v181 row_half_mirror row_mask:0xf bank_mask:0xa
	v_add_f32_dpp v182, v166, v166 row_mirror row_mask:0xf bank_mask:0x3
	s_nop 1
	v_add_f32_dpp v182, v174, v174 row_mirror row_mask:0xf bank_mask:0xc
	v_add_f32_dpp v186, v178, v178 row_half_mirror row_mask:0xf bank_mask:0x5
	s_nop 1
	v_add_f32_dpp v186, v182, v182 row_half_mirror row_mask:0xf bank_mask:0xa
	v_cndmask_b32_e64 v190, v184, v186, s[98:99]
	v_cndmask_b32_e64 v191, v186, v184, s[98:99]
	s_nop 1
	v_add_f32_dpp v188, v191, v190 quad_perm:[2,3,0,1] row_mask:0xf bank_mask:0xf
	v_add_f32_dpp v183, v167, v167 row_mirror row_mask:0xf bank_mask:0x3
	s_nop 1
	v_add_f32_dpp v183, v175, v175 row_mirror row_mask:0xf bank_mask:0xc
	v_add_f32_dpp v187, v179, v179 row_half_mirror row_mask:0xf bank_mask:0x5
	s_nop 1
	v_add_f32_dpp v187, v183, v183 row_half_mirror row_mask:0xf bank_mask:0xa
	s_waitcnt lgkmcnt(0)
	v_pk_mul_f32 v[12:13], v[12:13], v[20:21]
	v_pk_mul_f32 v[14:15], v[14:15], v[22:23]
	v_cndmask_b32_e64 v190, v185, v187, s[98:99]
	v_cndmask_b32_e64 v191, v187, v185, s[98:99]
	s_nop 1
	v_add_f32_dpp v189, v191, v190 quad_perm:[2,3,0,1] row_mask:0xf bank_mask:0xf
	v_cndmask_b32_e64 v190, v188, v189, s[100:101]
	v_cndmask_b32_e64 v191, v189, v188, s[100:101]
	s_nop 1
	v_add_f32_dpp v192, v191, v190 quad_perm:[1,0,3,2] row_mask:0xf bank_mask:0xf
	v_add_u32_e32 v196, 16, v5
	v_lshlrev_b32_e32 v194, 11, v196
	v_mov_b32_e32 v195, 0
	v_cvt_pk_bf16_f32 v193, v192, v192
	v_lshl_add_u64 v[194:195], v[6:7], 0, v[194:195]
	global_store_short v[194:195], v193, off offset:1024
	v_add_u32_e32 v5, 32, v5
	s_bitcmp1_b32 s22, 0
	s_cselect_b32 s4, s39, s38
	v_add_u32_e32 v2, s4, v2
	v_add_u32_e32 v3, s4, v3
	v_add_u32_e32 v4, s4, v4
	s_add_i32 s22, s22, 1
	s_cmpk_lt_i32 s22, 128
	s_waitcnt lgkmcnt(0)
	s_cbranch_scc1 .Lrw3_cloop
	global_store_dwordx4 v[8:9], v[12:15], off
	s_branch .LBB0_738
; __device__ __forceinline__ void rwkv_scan(const Params& p, LAS unsigned char* lds, int rowbase, int T, int h, int q4, const float* S0, float* Sout) {
;     ...
;     const bool ldr = w >= 4; const int lt = tid & 255, lstep = lt >> 4, lj = lt & 15;
;     f32x4 gd[2]; u32x2 gk[2], ga[2], gp[2], gr[2], gv[2];
;     auto gload = [&](int c) {
;         if (ldr) {
; #pragma unroll
;             for (int q = 0; q < 2; ++q) {
;                 const size_t row = (size_t)(rowbase + c * 32 + lstep + q * 16); const size_t o = row * 512 + h * 64 + lj * 4;
;                 gd[q] = *(const f32x4*)(decay + o); gk[q] = *(const u32x2*)(kk + o); ga[q] = *(const u32x2*)(kka + o); gp[q] = *(const u32x2*)(kp + o); gr[q] = *(const u32x2*)(rb + o);
;                 gv[q] = *(const u32x2*)(vb + row * 512 + h * 64 + q4 * 16 + (lj & 3) * 4);
;             }
;         }
;     };
.Lrw3_loader:
	s_sub_i32 s46, s46, 4
	v_and_b32_e32 v6, 15, v0
	v_lshrrev_b32_e32 v7, 4, v0
	s_lshl_b32 s4, s46, 5
	s_add_i32 s4, s4, s42
	v_lshl_add_u32 v8, v7, 3, s4
	v_lshlrev_b32_e32 v8, 9, v8
	s_lshl_b32 s4, s45, 6
	v_add_u32_e32 v8, s4, v8
	v_lshl_add_u32 v9, v6, 2, v8
	v_lshlrev_b32_e32 v24, 2, v9
	v_add_u32_e32 v25, 4096, v24
	v_add_u32_e32 v26, 8192, v24
	v_add_u32_e32 v27, 12288, v24
	v_lshlrev_b32_e32 v28, 1, v9
	v_add_u32_e32 v29, 4096, v28
	v_and_b32_e32 v10, 3, v6
	v_lshl_add_u32 v10, v10, 2, v8
	v_add_u32_e32 v10, s43, v10
	v_lshlrev_b32_e32 v30, 1, v10
	v_add_u32_e32 v31, 4096, v30
	s_and_b32 s4, s46, 1
	s_mul_i32 s4, s4, 35328
	v_mul_u32_u24_e32 v32, 2048, v7
	v_lshl_add_u32 v32, v6, 4, v32
	v_add_u32_e32 v32, s4, v32
	v_mul_u32_u24_e32 v33, 576, v6
	v_lshl_add_u32 v33, v7, 5, v33
	s_add_i32 s5, s4, 32768
	v_add_u32_e32 v33, s5, v33
	v_lshlrev_b32_e32 v34, 4, v6
	s_add_i32 s5, s4, 35072
	v_add_u32_e32 v34, s5, v34
	v_add_u32_e32 v35, 48, v0
	v_and_b32_e32 v35, 63, v35
	v_lshlrev_b32_e32 v35, 2, v35
	v_add_u32_e32 v36, 32, v0
	v_and_b32_e32 v36, 63, v36
	v_lshlrev_b32_e32 v36, 2, v36
	v_add_u32_e32 v37, 16, v0
	v_and_b32_e32 v37, 63, v37
	v_lshlrev_b32_e32 v37, 2, v37
	s_mov_b32 s98, 0xffff0000
	s_mov_b32 s99, 0xffffffff
	s_mov_b32 s100, 0
	s_mov_b32 s101, 0xffffffff
	s_mov_b32 s52, 0
	s_mov_b32 s53, 0xffff0000
	s_mov_b32 s30, 0x000f000f
	s_mov_b32 s31, 0x000f000f
	global_load_dwordx4 v[40:43], v24, s[90:91]
	global_load_dwordx4 v[44:47], v24, s[90:91] offset:2048
	global_load_dwordx4 v[48:51], v25, s[90:91]
	global_load_dwordx4 v[52:55], v25, s[90:91] offset:2048
	global_load_dwordx4 v[56:59], v26, s[90:91]
	global_load_dwordx4 v[60:63], v26, s[90:91] offset:2048
	global_load_dwordx4 v[64:67], v27, s[90:91]
	global_load_dwordx4 v[68:71], v27, s[90:91] offset:2048
	global_load_dwordx2 v[72:73], v28, s[6:7]
	global_load_dwordx2 v[88:89], v28, s[8:9]
	global_load_dwordx2 v[104:105], v28, s[10:11]
	global_load_dwordx2 v[120:121], v28, s[12:13]
	global_load_dwordx2 v[136:137], v30, s[16:17]
	global_load_dwordx2 v[74:75], v28, s[6:7] offset:1024
	global_load_dwordx2 v[90:91], v28, s[8:9] offset:1024
	global_load_dwordx2 v[106:107], v28, s[10:11] offset:1024
	global_load_dwordx2 v[122:123], v28, s[12:13] offset:1024
	global_load_dwordx2 v[138:139], v30, s[16:17] offset:1024
	global_load_dwordx2 v[76:77], v28, s[6:7] offset:2048
	global_load_dwordx2 v[92:93], v28, s[8:9] offset:2048
	global_load_dwordx2 v[108:109], v28, s[10:11] offset:2048
	global_load_dwordx2 v[124:125], v28, s[12:13] offset:2048
	global_load_dwordx2 v[140:141], v30, s[16:17] offset:2048
	global_load_dwordx2 v[78:79], v28, s[6:7] offset:3072
	global_load_dwordx2 v[94:95], v28, s[8:9] offset:3072
	global_load_dwordx2 v[110:111], v28, s[10:11] offset:3072
	global_load_dwordx2 v[126:127], v28, s[12:13] offset:3072
	global_load_dwordx2 v[142:143], v30, s[16:17] offset:3072
	global_load_dwordx2 v[80:81], v29, s[6:7]
	global_load_dwordx2 v[96:97], v29, s[8:9]
	global_load_dwordx2 v[112:113], v29, s[10:11]
	global_load_dwordx2 v[128:129], v29, s[12:13]
	global_load_dwordx2 v[144:145], v31, s[16:17]
	global_load_dwordx2 v[82:83], v29, s[6:7] offset:1024
	global_load_dwordx2 v[98:99], v29, s[8:9] offset:1024
	global_load_dwordx2 v[114:115], v29, s[10:11] offset:1024
	global_load_dwordx2 v[130:131], v29, s[12:13] offset:1024
	global_load_dwordx2 v[146:147], v31, s[16:17] offset:1024
	global_load_dwordx2 v[84:85], v29, s[6:7] offset:2048
	global_load_dwordx2 v[100:101], v29, s[8:9] offset:2048
	global_load_dwordx2 v[116:117], v29, s[10:11] offset:2048
	global_load_dwordx2 v[132:133], v29, s[12:13] offset:2048
	global_load_dwordx2 v[148:149], v31, s[16:17] offset:2048
	global_load_dwordx2 v[86:87], v29, s[6:7] offset:3072
	global_load_dwordx2 v[102:103], v29, s[8:9] offset:3072
	global_load_dwordx2 v[118:119], v29, s[10:11] offset:3072
	global_load_dwordx2 v[134:135], v29, s[12:13] offset:3072
	global_load_dwordx2 v[150:151], v31, s[16:17] offset:3072
	s_mov_b32 s50, 0
	s_cmp_eq_u32 s46, 0
	s_cselect_b32 s50, -1, 0
	s_cmp_lt_u32 s46, 2
	s_cbranch_scc1 .Lrw3_lead_done
	s_cmp_lt_u32 s50, 128
	s_cbranch_scc0 .Lrw3_nb1
	s_barrier
.Lrw3_nb1:
	s_add_i32 s50, s50, 1
	s_cmp_lt_u32 s46, 3
	s_cbranch_scc1 .Lrw3_lead_done
	s_cmp_lt_u32 s50, 128
	s_cbranch_scc0 .Lrw3_nb2
	s_barrier

; #define LAS __attribute__((address_space(3)))
; __device__ __forceinline__ float bf_lo(unsigned w) { return __uint_as_float(w << 16); }
; __device__ __forceinline__ float bf_hi(unsigned w) { return __uint_as_float(w & 0xffff0000u); }
; __device__ __forceinline__ void rwkv_scan(const Params& p, LAS unsigned char* lds, int rowbase, int T, int h, int q4, const float* S0, float* Sout) {
;     ...
;     auto gload = [&](int c) {
;         if (ldr) {
; #pragma unroll
;             for (int q = 0; q < 2; ++q) {
;                 const size_t row = (size_t)(rowbase + c * 32 + lstep + q * 16); const size_t o = row * 512 + h * 64 + lj * 4;
;                 gd[q] = *(const f32x4*)(decay + o); gk[q] = *(const u32x2*)(kk + o); ga[q] = *(const u32x2*)(kka + o); gp[q] = *(const u32x2*)(kp + o); gr[q] = *(const u32x2*)(rb + o);
;                 gv[q] = *(const u32x2*)(vb + row * 512 + h * 64 + q4 * 16 + (lj & 3) * 4);
;             }
;         }
;     };
;     auto up4 = [](const u32x2 x) { return (f32x4){bf_lo(x.x), bf_hi(x.x), bf_lo(x.y), bf_hi(x.y)}; };
;     float selv[16];
; #pragma unroll
;     for (int i = 0; i < 16; ++i) selv[i] = (seg == i) ? 1.0f : 0.0f;
;     const int nch = T / 32;
;     gload(0);
; #pragma unroll 1
;     for (int c = 0; c < nch; ++c) {
;         LAS unsigned char* b = lds + (c & 1) * BUF;
;         if (ldr) {
; #pragma unroll
;             for (int q = 0; q < 2; ++q) {
;                 const int st_ = lstep + q * 16;
;                 *(LAS f32x4*)(b + st_ * 256 + lj * 16) = gd[q];
;                 *(LAS f32x4*)(b + 8192 + st_ * 256 + lj * 16) = up4(gk[q]);
;                 *(LAS f32x4*)(b + 16384 + st_ * 256 + lj * 16) = up4(ga[q]);
;                 *(LAS f32x4*)(b + 24576 + st_ * 256 + lj * 16) = up4(gp[q]);
;                 *(LAS f32x4*)(b + 32768 + st_ * 256 + lj * 16) = up4(gr[q]);
;                 if (lj < 4) *(LAS f32x4*)(b + 40960 + st_ * 64 + lj * 16) = up4(gv[q]);
;             }
;         }
.Lrw3_lead_done:
.Lrw3_lloop:
	s_waitcnt vmcnt(0)
	v_mul_f32_e32 v44, v44, v40
	v_mul_f32_e32 v45, v45, v41
	v_mul_f32_e32 v46, v46, v42
	v_mul_f32_e32 v47, v47, v43
	v_mul_f32_e32 v48, v48, v44
	v_mul_f32_e32 v49, v49, v45
	v_mul_f32_e32 v50, v50, v46
	v_mul_f32_e32 v51, v51, v47
	v_mul_f32_e32 v52, v52, v48
	v_mul_f32_e32 v53, v53, v49
	v_mul_f32_e32 v54, v54, v50
	v_mul_f32_e32 v55, v55, v51
	v_mul_f32_e32 v56, v56, v52
	v_mul_f32_e32 v57, v57, v53
	v_mul_f32_e32 v58, v58, v54
	v_mul_f32_e32 v59, v59, v55
	v_mul_f32_e32 v60, v60, v56
	v_mul_f32_e32 v61, v61, v57
	v_mul_f32_e32 v62, v62, v58
	v_mul_f32_e32 v63, v63, v59
	v_mul_f32_e32 v64, v64, v60
	v_mul_f32_e32 v65, v65, v61
	v_mul_f32_e32 v66, v66, v62
	v_mul_f32_e32 v67, v67, v63
	v_mul_f32_e32 v68, v68, v64
	v_mul_f32_e32 v69, v69, v65
	v_mul_f32_e32 v70, v70, v66
	v_mul_f32_e32 v71, v71, v67
	ds_bpermute_b32 v188, v35, v68
	ds_bpermute_b32 v189, v35, v69
	ds_bpermute_b32 v190, v35, v70
	ds_bpermute_b32 v191, v35, v71
	ds_bpermute_b32 v192, v36, v68
	ds_bpermute_b32 v193, v36, v69
	ds_bpermute_b32 v194, v36, v70
	ds_bpermute_b32 v195, v36, v71
	ds_bpermute_b32 v196, v37, v68
	ds_bpermute_b32 v197, v37, v69
	ds_bpermute_b32 v198, v37, v70
	ds_bpermute_b32 v199, v37, v71
	s_waitcnt lgkmcnt(0)
	v_mov_b32_e32 v2, 1.0
	v_mov_b32_e32 v3, 1.0
	v_mov_b32_e32 v4, 1.0
	v_mov_b32_e32 v5, 1.0
	v_cndmask_b32_e64 v184, v2, v188, s[98:99]
	v_cndmask_b32_e64 v185, v3, v189, s[98:99]
	v_cndmask_b32_e64 v186, v4, v190, s[98:99]
	v_cndmask_b32_e64 v187, v5, v191, s[98:99]
	v_cndmask_b32_e64 v192, v2, v192, s[100:101]
	v_cndmask_b32_e64 v193, v3, v193, s[100:101]
	v_cndmask_b32_e64 v194, v4, v194, s[100:101]
	v_cndmask_b32_e64 v195, v5, v195, s[100:101]
	v_mul_f32_e32 v184, v184, v192
	v_mul_f32_e32 v185, v185, v193
	v_mul_f32_e32 v186, v186, v194
	v_mul_f32_e32 v187, v187, v195
	v_cndmask_b32_e64 v196, v2, v196, s[52:53]
	v_cndmask_b32_e64 v197, v3, v197, s[52:53]
	v_cndmask_b32_e64 v198, v4, v198, s[52:53]
	v_cndmask_b32_e64 v199, v5, v199, s[52:53]
	v_mul_f32_e32 v184, v184, v196
	v_mul_f32_e32 v185, v185, v197
	v_mul_f32_e32 v186, v186, v198
	v_mul_f32_e32 v187, v187, v199
	v_mul_f32_e32 v40, v40, v184
	v_mul_f32_e32 v41, v41, v185
	v_mul_f32_e32 v42, v42, v186
	v_mul_f32_e32 v43, v43, v187
	v_mul_f32_e32 v44, v44, v184
	v_mul_f32_e32 v45, v45, v185
	v_mul_f32_e32 v46, v46, v186
	v_mul_f32_e32 v47, v47, v187
	v_mul_f32_e32 v48, v48, v184
	v_mul_f32_e32 v49, v49, v185
	v_mul_f32_e32 v50, v50, v186
	v_mul_f32_e32 v51, v51, v187
	v_mul_f32_e32 v52, v52, v184
	v_mul_f32_e32 v53, v53, v185
	v_mul_f32_e32 v54, v54, v186
	v_mul_f32_e32 v55, v55, v187
	v_mul_f32_e32 v56, v56, v184
	v_mul_f32_e32 v57, v57, v185
	v_mul_f32_e32 v58, v58, v186
	v_mul_f32_e32 v59, v59, v187
	v_mul_f32_e32 v60, v60, v184
	v_mul_f32_e32 v61, v61, v185
	v_mul_f32_e32 v62, v62, v186
	v_mul_f32_e32 v63, v63, v187
	v_mul_f32_e32 v64, v64, v184
	v_mul_f32_e32 v65, v65, v185
	v_mul_f32_e32 v66, v66, v186
	v_mul_f32_e32 v67, v67, v187
	v_mul_f32_e32 v68, v68, v184
	v_mul_f32_e32 v69, v69, v185
	v_mul_f32_e32 v70, v70, v186
	v_mul_f32_e32 v71, v71, v187
	v_rcp_f32_e32 v152, v40
	v_rcp_f32_e32 v153, v41
	v_rcp_f32_e32 v154, v42
	v_rcp_f32_e32 v155, v43
	v_rcp_f32_e32 v156, v44
	v_rcp_f32_e32 v157, v45
	v_rcp_f32_e32 v158, v46
	v_rcp_f32_e32 v159, v47
	v_rcp_f32_e32 v160, v48
	v_rcp_f32_e32 v161, v49
	v_rcp_f32_e32 v162, v50
	v_rcp_f32_e32 v163, v51
	v_rcp_f32_e32 v164, v52
	v_rcp_f32_e32 v165, v53
	v_rcp_f32_e32 v166, v54
	v_rcp_f32_e32 v167, v55
	v_rcp_f32_e32 v168, v56
	v_rcp_f32_e32 v169, v57
	v_rcp_f32_e32 v170, v58
	v_rcp_f32_e32 v171, v59
	v_rcp_f32_e32 v172, v60
	v_rcp_f32_e32 v173, v61
	v_rcp_f32_e32 v174, v62
	v_rcp_f32_e32 v175, v63
	v_rcp_f32_e32 v176, v64
	v_rcp_f32_e32 v177, v65
	v_rcp_f32_e32 v178, v66
	v_rcp_f32_e32 v179, v67
	v_rcp_f32_e32 v180, v68
	v_rcp_f32_e32 v181, v69
	v_rcp_f32_e32 v182, v70
	v_rcp_f32_e32 v183, v71
	s_cmp_lt_u32 s50, 128
	s_cbranch_scc0 .Lrw3_nb3
	s_barrier
.Lrw3_nb3:
	s_add_i32 s50, s50, 1
	v_lshlrev_b32_e32 v6, 16, v72
	v_and_b32_e32 v7, 0xffff0000, v72
	v_lshlrev_b32_e32 v8, 16, v73
	v_and_b32_e32 v9, 0xffff0000, v73
	v_mul_f32_e32 v202, v6, v184
	v_mul_f32_e32 v203, v7, v185
	v_mul_f32_e32 v204, v8, v186
	v_mul_f32_e32 v205, v9, v187
	v_lshlrev_b32_e32 v10, 16, v88
	v_and_b32_e32 v11, 0xffff0000, v88
	v_lshlrev_b32_e32 v12, 16, v89
	v_and_b32_e32 v13, 0xffff0000, v89
	v_mul_f32_e32 v206, v10, v152
	v_mul_f32_e32 v207, v11, v153
	v_mul_f32_e32 v208, v12, v154
	v_mul_f32_e32 v209, v13, v155
	v_lshlrev_b32_e32 v6, 16, v104
	v_and_b32_e32 v7, 0xffff0000, v104
	v_lshlrev_b32_e32 v8, 16, v105
	v_and_b32_e32 v9, 0xffff0000, v105
	v_mul_f32_e32 v210, v6, v152
	v_mul_f32_e32 v211, v7, v153
	v_mul_f32_e32 v212, v8, v154
	v_mul_f32_e32 v213, v9, v155
	v_lshlrev_b32_e32 v10, 16, v120
	v_and_b32_e32 v11, 0xffff0000, v120
	v_lshlrev_b32_e32 v12, 16, v121
	v_and_b32_e32 v13, 0xffff0000, v121
	v_mul_f32_e32 v214, v10, v40
	v_mul_f32_e32 v215, v11, v41
	v_mul_f32_e32 v216, v12, v42
	v_mul_f32_e32 v217, v13, v43
	ds_write_b128 v32, v[202:205] offset:0
	ds_write_b128 v32, v[206:209] offset:8192
	ds_write_b128 v32, v[210:213] offset:16384
	ds_write_b128 v32, v[214:217] offset:24576
	v_lshlrev_b32_e32 v6, 16, v74
	v_and_b32_e32 v7, 0xffff0000, v74
	v_lshlrev_b32_e32 v8, 16, v75
	v_and_b32_e32 v9, 0xffff0000, v75
	v_mul_f32_e32 v218, v6, v40
	v_mul_f32_e32 v219, v7, v41
	v_mul_f32_e32 v220, v8, v42
	v_mul_f32_e32 v221, v9, v43
	v_lshlrev_b32_e32 v10, 16, v90
	v_and_b32_e32 v11, 0xffff0000, v90
	v_lshlrev_b32_e32 v12, 16, v91
	v_and_b32_e32 v13, 0xffff0000, v91
	v_mul_f32_e32 v222, v10, v156
	v_mul_f32_e32 v223, v11, v157
	v_mul_f32_e32 v224, v12, v158
	v_mul_f32_e32 v225, v13, v159
	v_lshlrev_b32_e32 v6, 16, v106
	v_and_b32_e32 v7, 0xffff0000, v106
	v_lshlrev_b32_e32 v8, 16, v107
	v_and_b32_e32 v9, 0xffff0000, v107
	v_mul_f32_e32 v226, v6, v156
	v_mul_f32_e32 v227, v7, v157
	v_mul_f32_e32 v228, v8, v158
	v_mul_f32_e32 v229, v9, v159
	v_lshlrev_b32_e32 v10, 16, v122
	v_and_b32_e32 v11, 0xffff0000, v122
	v_lshlrev_b32_e32 v12, 16, v123
	v_and_b32_e32 v13, 0xffff0000, v123
	v_mul_f32_e32 v230, v10, v44
	v_mul_f32_e32 v231, v11, v45
	v_mul_f32_e32 v232, v12, v46
	v_mul_f32_e32 v233, v13, v47
	ds_write_b128 v32, v[218:221] offset:256
	ds_write_b128 v32, v[222:225] offset:8448
	ds_write_b128 v32, v[226:229] offset:16640
	ds_write_b128 v32, v[230:233] offset:24832
	s_waitcnt lgkmcnt(4)
; #define LAS __attribute__((address_space(3)))
; __device__ __forceinline__ void rwkv_scan(const Params& p, LAS unsigned char* lds, int rowbase, int T, int h, int q4, const float* S0, float* Sout) {
;     ...
;         if (ldr) {
; #pragma unroll
;             for (int q = 0; q < 2; ++q) {
;                 const int st_ = lstep + q * 16;
;                 *(LAS f32x4*)(b + st_ * 256 + lj * 16) = gd[q];
;                 *(LAS f32x4*)(b + 8192 + st_ * 256 + lj * 16) = up4(gk[q]);
;                 *(LAS f32x4*)(b + 16384 + st_ * 256 + lj * 16) = up4(ga[q]);
;                 *(LAS f32x4*)(b + 24576 + st_ * 256 + lj * 16) = up4(gp[q]);
;                 *(LAS f32x4*)(b + 32768 + st_ * 256 + lj * 16) = up4(gr[q]);
;                 if (lj < 4) *(LAS f32x4*)(b + 40960 + st_ * 64 + lj * 16) = up4(gv[q]);
;             }
;         }
	v_lshlrev_b32_e32 v6, 16, v76
	v_and_b32_e32 v7, 0xffff0000, v76
	v_lshlrev_b32_e32 v8, 16, v77
	v_and_b32_e32 v9, 0xffff0000, v77
	v_mul_f32_e32 v202, v6, v44
	v_mul_f32_e32 v203, v7, v45
	v_mul_f32_e32 v204, v8, v46
	v_mul_f32_e32 v205, v9, v47
	v_lshlrev_b32_e32 v10, 16, v92
	v_and_b32_e32 v11, 0xffff0000, v92
	v_lshlrev_b32_e32 v12, 16, v93
	v_and_b32_e32 v13, 0xffff0000, v93
	v_mul_f32_e32 v206, v10, v160
	v_mul_f32_e32 v207, v11, v161
	v_mul_f32_e32 v208, v12, v162
	v_mul_f32_e32 v209, v13, v163
	v_lshlrev_b32_e32 v6, 16, v108
	v_and_b32_e32 v7, 0xffff0000, v108
	v_lshlrev_b32_e32 v8, 16, v109
	v_and_b32_e32 v9, 0xffff0000, v109
	v_mul_f32_e32 v210, v6, v160
	v_mul_f32_e32 v211, v7, v161
	v_mul_f32_e32 v212, v8, v162
	v_mul_f32_e32 v213, v9, v163
	v_lshlrev_b32_e32 v10, 16, v124
	v_and_b32_e32 v11, 0xffff0000, v124
	v_lshlrev_b32_e32 v12, 16, v125
	v_and_b32_e32 v13, 0xffff0000, v125
	v_mul_f32_e32 v214, v10, v48
	v_mul_f32_e32 v215, v11, v49
	v_mul_f32_e32 v216, v12, v50
	v_mul_f32_e32 v217, v13, v51
	ds_write_b128 v32, v[202:205] offset:512
	ds_write_b128 v32, v[206:209] offset:8704
	ds_write_b128 v32, v[210:213] offset:16896
	ds_write_b128 v32, v[214:217] offset:25088
	s_waitcnt lgkmcnt(4)
	v_lshlrev_b32_e32 v6, 16, v78
	v_and_b32_e32 v7, 0xffff0000, v78
	v_lshlrev_b32_e32 v8, 16, v79
	v_and_b32_e32 v9, 0xffff0000, v79
	v_mul_f32_e32 v218, v6, v48
	v_mul_f32_e32 v219, v7, v49
	v_mul_f32_e32 v220, v8, v50
	v_mul_f32_e32 v221, v9, v51
	v_lshlrev_b32_e32 v10, 16, v94
	v_and_b32_e32 v11, 0xffff0000, v94
	v_lshlrev_b32_e32 v12, 16, v95
	v_and_b32_e32 v13, 0xffff0000, v95
	v_mul_f32_e32 v222, v10, v164
	v_mul_f32_e32 v223, v11, v165
	v_mul_f32_e32 v224, v12, v166
	v_mul_f32_e32 v225, v13, v167
	v_lshlrev_b32_e32 v6, 16, v110
	v_and_b32_e32 v7, 0xffff0000, v110
	v_lshlrev_b32_e32 v8, 16, v111
	v_and_b32_e32 v9, 0xffff0000, v111
	v_mul_f32_e32 v226, v6, v164
	v_mul_f32_e32 v227, v7, v165
	v_mul_f32_e32 v228, v8, v166
	v_mul_f32_e32 v229, v9, v167
	v_lshlrev_b32_e32 v10, 16, v126
	v_and_b32_e32 v11, 0xffff0000, v126
	v_lshlrev_b32_e32 v12, 16, v127
	v_and_b32_e32 v13, 0xffff0000, v127
	v_mul_f32_e32 v230, v10, v52
	v_mul_f32_e32 v231, v11, v53
	v_mul_f32_e32 v232, v12, v54
	v_mul_f32_e32 v233, v13, v55
	ds_write_b128 v32, v[218:221] offset:768
	ds_write_b128 v32, v[222:225] offset:8960
	ds_write_b128 v32, v[226:229] offset:17152
	ds_write_b128 v32, v[230:233] offset:25344
	s_waitcnt lgkmcnt(4)
	v_lshlrev_b32_e32 v6, 16, v80
	v_and_b32_e32 v7, 0xffff0000, v80
	v_lshlrev_b32_e32 v8, 16, v81
	v_and_b32_e32 v9, 0xffff0000, v81
	v_mul_f32_e32 v202, v6, v52
	v_mul_f32_e32 v203, v7, v53
	v_mul_f32_e32 v204, v8, v54
	v_mul_f32_e32 v205, v9, v55
	v_lshlrev_b32_e32 v10, 16, v96
	v_and_b32_e32 v11, 0xffff0000, v96
	v_lshlrev_b32_e32 v12, 16, v97
	v_and_b32_e32 v13, 0xffff0000, v97
	v_mul_f32_e32 v206, v10, v168
	v_mul_f32_e32 v207, v11, v169
	v_mul_f32_e32 v208, v12, v170
	v_mul_f32_e32 v209, v13, v171
	v_lshlrev_b32_e32 v6, 16, v112
	v_and_b32_e32 v7, 0xffff0000, v112
	v_lshlrev_b32_e32 v8, 16, v113
	v_and_b32_e32 v9, 0xffff0000, v113
	v_mul_f32_e32 v210, v6, v168
	v_mul_f32_e32 v211, v7, v169
	v_mul_f32_e32 v212, v8, v170
	v_mul_f32_e32 v213, v9, v171
	v_lshlrev_b32_e32 v10, 16, v128
	v_and_b32_e32 v11, 0xffff0000, v128
	v_lshlrev_b32_e32 v12, 16, v129
	v_and_b32_e32 v13, 0xffff0000, v129
	v_mul_f32_e32 v214, v10, v56
	v_mul_f32_e32 v215, v11, v57
	v_mul_f32_e32 v216, v12, v58
	v_mul_f32_e32 v217, v13, v59
	ds_write_b128 v32, v[202:205] offset:1024
	ds_write_b128 v32, v[206:209] offset:9216
	ds_write_b128 v32, v[210:213] offset:17408
	ds_write_b128 v32, v[214:217] offset:25600
	s_waitcnt lgkmcnt(4)
	v_lshlrev_b32_e32 v6, 16, v82
	v_and_b32_e32 v7, 0xffff0000, v82
	v_lshlrev_b32_e32 v8, 16, v83
	v_and_b32_e32 v9, 0xffff0000, v83
	v_mul_f32_e32 v218, v6, v56
	v_mul_f32_e32 v219, v7, v57
	v_mul_f32_e32 v220, v8, v58
	v_mul_f32_e32 v221, v9, v59
	v_lshlrev_b32_e32 v10, 16, v98
	v_and_b32_e32 v11, 0xffff0000, v98
	v_lshlrev_b32_e32 v12, 16, v99
	v_and_b32_e32 v13, 0xffff0000, v99
	v_mul_f32_e32 v222, v10, v172
	v_mul_f32_e32 v223, v11, v173
	v_mul_f32_e32 v224, v12, v174
	v_mul_f32_e32 v225, v13, v175
	v_lshlrev_b32_e32 v6, 16, v114
	v_and_b32_e32 v7, 0xffff0000, v114
	v_lshlrev_b32_e32 v8, 16, v115
	v_and_b32_e32 v9, 0xffff0000, v115
	v_mul_f32_e32 v226, v6, v172
	v_mul_f32_e32 v227, v7, v173
	v_mul_f32_e32 v228, v8, v174
	v_mul_f32_e32 v229, v9, v175
	v_lshlrev_b32_e32 v10, 16, v130
	v_and_b32_e32 v11, 0xffff0000, v130
	v_lshlrev_b32_e32 v12, 16, v131
	v_and_b32_e32 v13, 0xffff0000, v131
	v_mul_f32_e32 v230, v10, v60
	v_mul_f32_e32 v231, v11, v61
	v_mul_f32_e32 v232, v12, v62
	v_mul_f32_e32 v233, v13, v63
	ds_write_b128 v32, v[218:221] offset:1280
	ds_write_b128 v32, v[222:225] offset:9472
	ds_write_b128 v32, v[226:229] offset:17664
	ds_write_b128 v32, v[230:233] offset:25856
	s_waitcnt lgkmcnt(4)
	v_lshlrev_b32_e32 v6, 16, v84
	v_and_b32_e32 v7, 0xffff0000, v84
	v_lshlrev_b32_e32 v8, 16, v85
	v_and_b32_e32 v9, 0xffff0000, v85
	v_mul_f32_e32 v202, v6, v60
	v_mul_f32_e32 v203, v7, v61
	v_mul_f32_e32 v204, v8, v62
	v_mul_f32_e32 v205, v9, v63
	v_lshlrev_b32_e32 v10, 16, v100
	v_and_b32_e32 v11, 0xffff0000, v100
	v_lshlrev_b32_e32 v12, 16, v101
	v_and_b32_e32 v13, 0xffff0000, v101
	v_mul_f32_e32 v206, v10, v176
	v_mul_f32_e32 v207, v11, v177
	v_mul_f32_e32 v208, v12, v178
	v_mul_f32_e32 v209, v13, v179
	v_lshlrev_b32_e32 v6, 16, v116
	v_and_b32_e32 v7, 0xffff0000, v116
	v_lshlrev_b32_e32 v8, 16, v117
	v_and_b32_e32 v9, 0xffff0000, v117
	v_mul_f32_e32 v210, v6, v176
	v_mul_f32_e32 v211, v7, v177
	v_mul_f32_e32 v212, v8, v178
	v_mul_f32_e32 v213, v9, v179
	v_lshlrev_b32_e32 v10, 16, v132
	v_and_b32_e32 v11, 0xffff0000, v132
	v_lshlrev_b32_e32 v12, 16, v133
	v_and_b32_e32 v13, 0xffff0000, v133
	v_mul_f32_e32 v214, v10, v64
	v_mul_f32_e32 v215, v11, v65
	v_mul_f32_e32 v216, v12, v66
	v_mul_f32_e32 v217, v13, v67
	ds_write_b128 v32, v[202:205] offset:1536
	ds_write_b128 v32, v[206:209] offset:9728
	ds_write_b128 v32, v[210:213] offset:17920
	ds_write_b128 v32, v[214:217] offset:26112
	s_waitcnt lgkmcnt(4)
; #define LAS __attribute__((address_space(3)))
; __device__ __forceinline__ void rwkv_scan(const Params& p, LAS unsigned char* lds, int rowbase, int T, int h, int q4, const float* S0, float* Sout) {
;     ...
;         if (ldr) {
; #pragma unroll
;             for (int q = 0; q < 2; ++q) {
;                 const int st_ = lstep + q * 16;
;                 *(LAS f32x4*)(b + st_ * 256 + lj * 16) = gd[q];
;                 *(LAS f32x4*)(b + 8192 + st_ * 256 + lj * 16) = up4(gk[q]);
;                 *(LAS f32x4*)(b + 16384 + st_ * 256 + lj * 16) = up4(ga[q]);
;                 *(LAS f32x4*)(b + 24576 + st_ * 256 + lj * 16) = up4(gp[q]);
;                 *(LAS f32x4*)(b + 32768 + st_ * 256 + lj * 16) = up4(gr[q]);
;                 if (lj < 4) *(LAS f32x4*)(b + 40960 + st_ * 64 + lj * 16) = up4(gv[q]);
;             }
;         }
;         __syncthreads();
;         if (c + 1 < nch) gload(c + 1);
	v_lshlrev_b32_e32 v6, 16, v86
	v_and_b32_e32 v7, 0xffff0000, v86
	v_lshlrev_b32_e32 v8, 16, v87
	v_and_b32_e32 v9, 0xffff0000, v87
	v_mul_f32_e32 v218, v6, v64
	v_mul_f32_e32 v219, v7, v65
	v_mul_f32_e32 v220, v8, v66
	v_mul_f32_e32 v221, v9, v67
	v_lshlrev_b32_e32 v10, 16, v102
	v_and_b32_e32 v11, 0xffff0000, v102
	v_lshlrev_b32_e32 v12, 16, v103
	v_and_b32_e32 v13, 0xffff0000, v103
	v_mul_f32_e32 v222, v10, v180
	v_mul_f32_e32 v223, v11, v181
	v_mul_f32_e32 v224, v12, v182
	v_mul_f32_e32 v225, v13, v183
	v_lshlrev_b32_e32 v6, 16, v118
	v_and_b32_e32 v7, 0xffff0000, v118
	v_lshlrev_b32_e32 v8, 16, v119
	v_and_b32_e32 v9, 0xffff0000, v119
	v_mul_f32_e32 v226, v6, v180
	v_mul_f32_e32 v227, v7, v181
	v_mul_f32_e32 v228, v8, v182
	v_mul_f32_e32 v229, v9, v183
	v_lshlrev_b32_e32 v10, 16, v134
	v_and_b32_e32 v11, 0xffff0000, v134
	v_lshlrev_b32_e32 v12, 16, v135
	v_and_b32_e32 v13, 0xffff0000, v135
	v_mul_f32_e32 v230, v10, v68
	v_mul_f32_e32 v231, v11, v69
	v_mul_f32_e32 v232, v12, v70
	v_mul_f32_e32 v233, v13, v71
	ds_write_b128 v32, v[218:221] offset:1792
	ds_write_b128 v32, v[222:225] offset:9984
	ds_write_b128 v32, v[226:229] offset:18176
	ds_write_b128 v32, v[230:233] offset:26368
	s_mov_b64 exec, s[52:53]
	ds_write_b128 v34, v[68:71]
	s_mov_b64 exec, -1
	s_waitcnt lgkmcnt(0)
	v_lshlrev_b32_e32 v202, 16, v136
	v_and_b32_e32 v210, 0xffff0000, v136
	v_lshlrev_b32_e32 v218, 16, v137
	v_and_b32_e32 v226, 0xffff0000, v137
	v_lshlrev_b32_e32 v203, 16, v138
	v_and_b32_e32 v211, 0xffff0000, v138
	v_lshlrev_b32_e32 v219, 16, v139
	v_and_b32_e32 v227, 0xffff0000, v139
	v_lshlrev_b32_e32 v204, 16, v140
	v_and_b32_e32 v212, 0xffff0000, v140
	v_lshlrev_b32_e32 v220, 16, v141
	v_and_b32_e32 v228, 0xffff0000, v141
	v_lshlrev_b32_e32 v205, 16, v142
	v_and_b32_e32 v213, 0xffff0000, v142
	v_lshlrev_b32_e32 v221, 16, v143
	v_and_b32_e32 v229, 0xffff0000, v143
	v_lshlrev_b32_e32 v206, 16, v144
	v_and_b32_e32 v214, 0xffff0000, v144
	v_lshlrev_b32_e32 v222, 16, v145
	v_and_b32_e32 v230, 0xffff0000, v145
	v_lshlrev_b32_e32 v207, 16, v146
	v_and_b32_e32 v215, 0xffff0000, v146
	v_lshlrev_b32_e32 v223, 16, v147
	v_and_b32_e32 v231, 0xffff0000, v147
	v_lshlrev_b32_e32 v208, 16, v148
	v_and_b32_e32 v216, 0xffff0000, v148
	v_lshlrev_b32_e32 v224, 16, v149
	v_and_b32_e32 v232, 0xffff0000, v149
	v_lshlrev_b32_e32 v209, 16, v150
	v_and_b32_e32 v217, 0xffff0000, v150
	v_lshlrev_b32_e32 v225, 16, v151
	v_and_b32_e32 v233, 0xffff0000, v151
	s_mov_b64 exec, s[30:31]
	ds_write_b128 v33, v[202:205] offset:0
	ds_write_b128 v33, v[206:209] offset:16
	ds_write_b128 v33, v[210:213] offset:144
	ds_write_b128 v33, v[214:217] offset:160
	ds_write_b128 v33, v[218:221] offset:288
	ds_write_b128 v33, v[222:225] offset:304
	ds_write_b128 v33, v[226:229] offset:432
	ds_write_b128 v33, v[230:233] offset:448
	s_mov_b64 exec, -1
	s_waitcnt lgkmcnt(0)
	s_cmp_lt_u32 s50, 128
	s_cbranch_scc0 .Lrw3_nb4
	s_barrier
.Lrw3_nb4:
	s_add_i32 s50, s50, 1
	v_add_u32_e32 v24, 0x40000, v24
	v_add_u32_e32 v25, 0x40000, v25
	v_add_u32_e32 v26, 0x40000, v26
	v_add_u32_e32 v27, 0x40000, v27
	v_add_u32_e32 v28, 0x20000, v28
	v_add_u32_e32 v29, 0x20000, v29
	v_add_u32_e32 v30, 0x20000, v30
	v_add_u32_e32 v31, 0x20000, v31
	global_load_dwordx4 v[40:43], v24, s[90:91]
	global_load_dwordx4 v[44:47], v24, s[90:91] offset:2048
	global_load_dwordx4 v[48:51], v25, s[90:91]
	global_load_dwordx4 v[52:55], v25, s[90:91] offset:2048
	global_load_dwordx4 v[56:59], v26, s[90:91]
	global_load_dwordx4 v[60:63], v26, s[90:91] offset:2048
	global_load_dwordx4 v[64:67], v27, s[90:91]
	global_load_dwordx4 v[68:71], v27, s[90:91] offset:2048
	global_load_dwordx2 v[72:73], v28, s[6:7]
	global_load_dwordx2 v[88:89], v28, s[8:9]
	global_load_dwordx2 v[104:105], v28, s[10:11]
	global_load_dwordx2 v[120:121], v28, s[12:13]
	global_load_dwordx2 v[136:137], v30, s[16:17]
	global_load_dwordx2 v[74:75], v28, s[6:7] offset:1024
	global_load_dwordx2 v[90:91], v28, s[8:9] offset:1024
	global_load_dwordx2 v[106:107], v28, s[10:11] offset:1024
	global_load_dwordx2 v[122:123], v28, s[12:13] offset:1024
	global_load_dwordx2 v[138:139], v30, s[16:17] offset:1024
	global_load_dwordx2 v[76:77], v28, s[6:7] offset:2048
	global_load_dwordx2 v[92:93], v28, s[8:9] offset:2048
	global_load_dwordx2 v[108:109], v28, s[10:11] offset:2048
	global_load_dwordx2 v[124:125], v28, s[12:13] offset:2048
	global_load_dwordx2 v[140:141], v30, s[16:17] offset:2048
	global_load_dwordx2 v[78:79], v28, s[6:7] offset:3072
	global_load_dwordx2 v[94:95], v28, s[8:9] offset:3072
	global_load_dwordx2 v[110:111], v28, s[10:11] offset:3072
	global_load_dwordx2 v[126:127], v28, s[12:13] offset:3072
	global_load_dwordx2 v[142:143], v30, s[16:17] offset:3072
	global_load_dwordx2 v[80:81], v29, s[6:7]
	global_load_dwordx2 v[96:97], v29, s[8:9]
	global_load_dwordx2 v[112:113], v29, s[10:11]
	global_load_dwordx2 v[128:129], v29, s[12:13]
	global_load_dwordx2 v[144:145], v31, s[16:17]
	global_load_dwordx2 v[82:83], v29, s[6:7] offset:1024
	global_load_dwordx2 v[98:99], v29, s[8:9] offset:1024
	global_load_dwordx2 v[114:115], v29, s[10:11] offset:1024
	global_load_dwordx2 v[130:131], v29, s[12:13] offset:1024
	global_load_dwordx2 v[146:147], v31, s[16:17] offset:1024
	global_load_dwordx2 v[84:85], v29, s[6:7] offset:2048
	global_load_dwordx2 v[100:101], v29, s[8:9] offset:2048
	global_load_dwordx2 v[116:117], v29, s[10:11] offset:2048
	global_load_dwordx2 v[132:133], v29, s[12:13] offset:2048
	global_load_dwordx2 v[148:149], v31, s[16:17] offset:2048
	global_load_dwordx2 v[86:87], v29, s[6:7] offset:3072
	global_load_dwordx2 v[102:103], v29, s[8:9] offset:3072
	global_load_dwordx2 v[118:119], v29, s[10:11] offset:3072
	global_load_dwordx2 v[134:135], v29, s[12:13] offset:3072
	global_load_dwordx2 v[150:151], v31, s[16:17] offset:3072
	s_cmp_lt_u32 s50, 128
	s_cbranch_scc0 .Lrw3_nb5
	s_barrier
.Lrw3_nb5:
	s_add_i32 s50, s50, 1
	s_cmp_lt_u32 s50, 128
	s_cbranch_scc0 .Lrw3_nb6
	s_barrier
.Lrw3_nb6:
	s_add_i32 s50, s50, 1
	s_add_i32 s22, s22, 1
	s_cmpk_lt_i32 s22, 32
	s_cbranch_scc1 .Lrw3_lloop
	s_cmp_lt_u32 s50, 128
	s_cbranch_scc0 .Lrw3_nb7
	s_barrier
.Lrw3_nb7:
	s_add_i32 s50, s50, 1
	s_waitcnt vmcnt(0)
	s_branch .LBB0_738
